# v42 + fused-LN stats: 78 dead lgkmcnt(0) waits (left over from the removed ds_bpermutes) deleted
# speedup vs baseline: 1.0004x; 1.0004x over previous
.LBB0_656:
	s_lshl_b32 s26, s25, 8
	s_add_i32 s1, s26, s45
	s_lshl_b32 s0, s12, 5
	v_or_b32_e32 v130, s1, v146
	s_lshl_b32 s1, s84, 8
	v_lshrrev_b32_e32 v131, 1, v164
	s_or_b32 s0, s1, s0
	v_and_or_b32 v162, v131, 24, s0
	v_ashrrev_i32_e32 v163, 31, v162
	v_ashrrev_i32_e32 v131, 31, v130
	v_lshl_add_u64 v[132:133], v[162:163], 1, s[34:35]
	v_lshlrev_b64 v[134:135], 12, v[130:131]
	v_lshl_add_u64 v[146:147], v[132:133], 0, v[134:135]
	v_or_b32_e32 v134, 16, v130
	v_ashrrev_i32_e32 v135, 31, v134
	v_lshlrev_b64 v[134:135], 12, v[134:135]
	v_lshl_add_u64 v[134:135], v[132:133], 0, v[134:135]
	s_barrier
	global_load_dwordx4 v[148:151], v[146:147], off
	global_load_dwordx4 v[152:155], v[146:147], off offset:256
	global_load_dwordx4 v[156:159], v[134:135], off
	global_load_dwordx4 v[168:171], v[134:135], off offset:256
	v_or_b32_e32 v134, 32, v130
	v_or_b32_e32 v130, 48, v130
	v_ashrrev_i32_e32 v135, 31, v134
	v_ashrrev_i32_e32 v131, 31, v130
	v_lshlrev_b64 v[134:135], 12, v[134:135]
	v_lshlrev_b64 v[130:131], 12, v[130:131]
	v_lshl_add_u64 v[134:135], v[132:133], 0, v[134:135]
	v_lshl_add_u64 v[130:131], v[132:133], 0, v[130:131]
	global_load_dwordx4 v[142:145], v[134:135], off
	global_load_dwordx4 v[138:141], v[134:135], off offset:256
	s_nop 0
	global_load_dwordx4 v[134:137], v[130:131], off
	s_nop 0
	global_load_dwordx4 v[130:133], v[130:131], off offset:256
	s_mov_b32 s18, 0x3fd744fd
	s_mov_b64 s[0:1], 0x80000
	v_and_b32_e32 v167, 64, v219
	v_xor_b32_e32 v165, 16, v219
	v_add_u32_e32 v167, 64, v167
	v_and_b32_e32 v166, 63, v164
	s_waitcnt vmcnt(0)
	s_nop 0
	v_lshlrev_b32_e32 v160, 16, v148
	v_and_b32_e32 v161, 0xffff0000, v148
	v_lshlrev_b32_e32 v148, 16, v149
	v_and_b32_e32 v149, 0xffff0000, v149
	v_pk_fma_f32 v[92:93], v[148:149], s[18:19], v[92:93] op_sel_hi:[1,0,1]
	v_lshlrev_b32_e32 v148, 16, v150
	v_and_b32_e32 v149, 0xffff0000, v150
	v_pk_fma_f32 v[94:95], v[148:149], s[18:19], v[94:95] op_sel_hi:[1,0,1]
	v_lshlrev_b32_e32 v148, 16, v152
	v_and_b32_e32 v149, 0xffff0000, v152
	v_pk_fma_f32 v[10:11], v[148:149], s[18:19], v[10:11] op_sel_hi:[1,0,1]
	v_lshlrev_b32_e32 v148, 16, v154
	v_and_b32_e32 v149, 0xffff0000, v154
	v_pk_fma_f32 v[14:15], v[148:149], s[18:19], v[14:15] op_sel_hi:[1,0,1]
	v_lshlrev_b32_e32 v148, 16, v156
	v_and_b32_e32 v149, 0xffff0000, v156
	v_pk_fma_f32 v[102:103], v[148:149], s[18:19], v[102:103] op_sel_hi:[1,0,1]
	v_lshlrev_b32_e32 v148, 16, v158
	v_and_b32_e32 v149, 0xffff0000, v158
	v_pk_fma_f32 v[106:107], v[148:149], s[18:19], v[106:107] op_sel_hi:[1,0,1]
	v_lshlrev_b32_e32 v148, 16, v168
	v_and_b32_e32 v149, 0xffff0000, v168
	v_pk_fma_f32 v[26:27], v[148:149], s[18:19], v[26:27] op_sel_hi:[1,0,1]
	v_lshlrev_b32_e32 v148, 16, v170
	v_and_b32_e32 v149, 0xffff0000, v170
	v_pk_fma_f32 v[38:39], v[148:149], s[18:19], v[38:39] op_sel_hi:[1,0,1]
	v_lshlrev_b32_e32 v148, 16, v142
	v_and_b32_e32 v149, 0xffff0000, v142
	v_lshlrev_b32_e32 v142, 16, v143
	v_and_b32_e32 v143, 0xffff0000, v143
	v_pk_fma_f32 v[116:117], v[142:143], s[18:19], v[116:117] op_sel_hi:[1,0,1]
	v_lshlrev_b32_e32 v142, 16, v144
	v_and_b32_e32 v143, 0xffff0000, v144
	v_pk_fma_f32 v[118:119], v[142:143], s[18:19], v[118:119] op_sel_hi:[1,0,1]
	v_lshlrev_b32_e32 v142, 16, v138
	v_and_b32_e32 v143, 0xffff0000, v138
	v_lshlrev_b32_e32 v138, 16, v139
	v_and_b32_e32 v139, 0xffff0000, v139
	v_pk_fma_f32 v[60:61], v[138:139], s[18:19], v[60:61] op_sel_hi:[1,0,1]
	v_lshlrev_b32_e32 v138, 16, v140
	v_and_b32_e32 v139, 0xffff0000, v140
	v_lshlrev_b32_e32 v150, 16, v151
	v_and_b32_e32 v151, 0xffff0000, v151
	v_pk_fma_f32 v[62:63], v[138:139], s[18:19], v[62:63] op_sel_hi:[1,0,1]
	v_lshlrev_b32_e32 v138, 16, v134
	v_and_b32_e32 v139, 0xffff0000, v134
	v_lshlrev_b32_e32 v134, 16, v135
	v_and_b32_e32 v135, 0xffff0000, v135
	v_pk_fma_f32 v[96:97], v[150:151], s[18:19], v[96:97] op_sel_hi:[1,0,1]
	v_lshlrev_b32_e32 v150, 16, v153
	v_and_b32_e32 v151, 0xffff0000, v153
	v_pk_fma_f32 v[124:125], v[134:135], s[18:19], v[124:125] op_sel_hi:[1,0,1]
	v_lshlrev_b32_e32 v134, 16, v136
	v_and_b32_e32 v135, 0xffff0000, v136
	v_pk_fma_f32 v[12:13], v[150:151], s[18:19], v[12:13] op_sel_hi:[1,0,1]
	v_lshlrev_b32_e32 v150, 16, v155
	v_and_b32_e32 v151, 0xffff0000, v155
	v_pk_fma_f32 v[126:127], v[134:135], s[18:19], v[126:127] op_sel_hi:[1,0,1]
	v_lshlrev_b32_e32 v134, 16, v130
	v_and_b32_e32 v135, 0xffff0000, v130
	v_lshlrev_b32_e32 v130, 16, v131
	v_and_b32_e32 v131, 0xffff0000, v131
	v_pk_fma_f32 v[16:17], v[150:151], s[18:19], v[16:17] op_sel_hi:[1,0,1]
	v_lshlrev_b32_e32 v150, 16, v157
	v_and_b32_e32 v151, 0xffff0000, v157
	v_pk_fma_f32 v[76:77], v[130:131], s[18:19], v[76:77] op_sel_hi:[1,0,1]
	v_pk_fma_f32 v[74:75], v[134:135], s[18:19], v[74:75] op_sel_hi:[1,0,1]
	v_lshlrev_b32_e32 v130, 16, v132
	v_and_b32_e32 v131, 0xffff0000, v132
	v_lshl_add_u64 v[134:135], v[146:147], 0, s[0:1]
	s_mov_b32 s0, 0x80000
	v_pk_fma_f32 v[104:105], v[150:151], s[18:19], v[104:105] op_sel_hi:[1,0,1]
	v_lshlrev_b32_e32 v150, 16, v159
	v_and_b32_e32 v151, 0xffff0000, v159
	v_pk_fma_f32 v[78:79], v[130:131], s[18:19], v[78:79] op_sel_hi:[1,0,1]
	v_add_co_u32_e32 v130, vcc, s0, v146
	s_mov_b64 s[0:1], 0x90000
	v_pk_fma_f32 v[108:109], v[150:151], s[18:19], v[108:109] op_sel_hi:[1,0,1]
	v_lshlrev_b32_e32 v150, 16, v169
	v_and_b32_e32 v151, 0xffff0000, v169
	v_lshlrev_b32_e32 v140, 16, v141
	v_and_b32_e32 v141, 0xffff0000, v141
	v_pk_fma_f32 v[122:123], v[138:139], s[18:19], v[122:123] op_sel_hi:[1,0,1]
	v_addc_co_u32_e32 v131, vcc, 0, v147, vcc
	v_lshl_add_u64 v[138:139], v[146:147], 0, s[0:1]
	s_mov_b32 s0, 0x90000
	v_pk_fma_f32 v[28:29], v[150:151], s[18:19], v[28:29] op_sel_hi:[1,0,1]
	v_lshlrev_b32_e32 v150, 16, v171
	v_and_b32_e32 v151, 0xffff0000, v171
	v_lshlrev_b32_e32 v144, 16, v145
	v_and_b32_e32 v145, 0xffff0000, v145
	v_pk_fma_f32 v[64:65], v[140:141], s[18:19], v[64:65] op_sel_hi:[1,0,1]
	v_lshlrev_b32_e32 v136, 16, v137
	v_and_b32_e32 v137, 0xffff0000, v137
	v_lshlrev_b32_e32 v132, 16, v133
	v_and_b32_e32 v133, 0xffff0000, v133
	v_add_co_u32_e32 v140, vcc, s0, v146
	v_pk_fma_f32 v[90:91], v[160:161], s[18:19], v[90:91] op_sel_hi:[1,0,1]
	v_pk_fma_f32 v[40:41], v[150:151], s[18:19], v[40:41] op_sel_hi:[1,0,1]
	v_pk_fma_f32 v[114:115], v[148:149], s[18:19], v[114:115] op_sel_hi:[1,0,1]
	v_pk_fma_f32 v[120:121], v[144:145], s[18:19], v[120:121] op_sel_hi:[1,0,1]
	v_pk_fma_f32 v[58:59], v[142:143], s[18:19], v[58:59] op_sel_hi:[1,0,1]
	v_pk_fma_f32 v[128:129], v[136:137], s[18:19], v[128:129] op_sel_hi:[1,0,1]
	v_pk_fma_f32 v[80:81], v[132:133], s[18:19], v[80:81] op_sel_hi:[1,0,1]
	v_addc_co_u32_e32 v141, vcc, 0, v147, vcc
	s_mov_b64 s[0:1], 0xa0000
	global_load_dwordx4 v[130:133], v[130:131], off
	s_nop 0
	global_load_dwordx4 v[134:137], v[134:135], off offset:256
	s_nop 0
	global_load_dwordx4 v[150:153], v[140:141], off
	global_load_dwordx4 v[154:157], v[138:139], off offset:256
	v_lshl_add_u64 v[138:139], v[146:147], 0, s[0:1]
	s_mov_b32 s0, 0xa0000
	v_add_co_u32_e32 v140, vcc, s0, v146
	s_mov_b64 s[0:1], 0xb0000
	s_nop 0
	v_addc_co_u32_e32 v141, vcc, 0, v147, vcc
	global_load_dwordx4 v[158:161], v[140:141], off
	global_load_dwordx4 v[168:171], v[138:139], off offset:256
	v_lshl_add_u64 v[138:139], v[146:147], 0, s[0:1]
	s_mov_b32 s0, 0xb0000
	v_add_co_u32_e32 v140, vcc, s0, v146
	v_mov_b32_e32 v172, v94
	s_nop 0
	v_addc_co_u32_e32 v141, vcc, 0, v147, vcc
	global_load_dwordx4 v[140:143], v[140:141], off
	s_nop 0
	global_load_dwordx4 v[146:149], v[138:139], off offset:256
	s_waitcnt vmcnt(0)
	s_nop 0
	v_lshlrev_b32_e32 v138, 16, v130
	v_and_b32_e32 v139, 0xffff0000, v130
	v_lshlrev_b32_e32 v130, 16, v131
	v_and_b32_e32 v131, 0xffff0000, v131
	v_pk_fma_f32 v[112:113], v[130:131], s[18:19], v[112:113] op_sel_hi:[1,0,1]
	v_lshlrev_b32_e32 v130, 16, v132
	v_and_b32_e32 v131, 0xffff0000, v132
	v_lshlrev_b32_e32 v132, 16, v133
	v_and_b32_e32 v133, 0xffff0000, v133
	v_pk_fma_f32 v[98:99], v[130:131], s[18:19], v[98:99] op_sel_hi:[1,0,1]
	v_lshlrev_b32_e32 v130, 16, v134
	v_and_b32_e32 v131, 0xffff0000, v134
	v_pk_fma_f32 v[100:101], v[132:133], s[18:19], v[100:101] op_sel_hi:[1,0,1]
	v_lshlrev_b32_e32 v132, 16, v135
	v_and_b32_e32 v133, 0xffff0000, v135
	v_pk_fma_f32 v[86:87], v[130:131], s[18:19], v[86:87] op_sel_hi:[1,0,1]
	v_lshlrev_b32_e32 v130, 16, v136
	v_and_b32_e32 v131, 0xffff0000, v136
	v_pk_fma_f32 v[88:89], v[132:133], s[18:19], v[88:89] op_sel_hi:[1,0,1]
	v_lshlrev_b32_e32 v132, 16, v137
	v_and_b32_e32 v133, 0xffff0000, v137
	v_pk_fma_f32 v[70:71], v[130:131], s[18:19], v[70:71] op_sel_hi:[1,0,1]
	v_lshlrev_b32_e32 v130, 16, v150
	v_and_b32_e32 v131, 0xffff0000, v150
	v_pk_fma_f32 v[72:73], v[132:133], s[18:19], v[72:73] op_sel_hi:[1,0,1]
	v_lshlrev_b32_e32 v132, 16, v151
	v_and_b32_e32 v133, 0xffff0000, v151
	v_pk_fma_f32 v[82:83], v[130:131], s[18:19], v[82:83] op_sel_hi:[1,0,1]
	v_lshlrev_b32_e32 v130, 16, v152
	v_and_b32_e32 v131, 0xffff0000, v152
	v_pk_fma_f32 v[84:85], v[132:133], s[18:19], v[84:85] op_sel_hi:[1,0,1]
	v_lshlrev_b32_e32 v132, 16, v153
	v_and_b32_e32 v133, 0xffff0000, v153
	v_pk_fma_f32 v[66:67], v[130:131], s[18:19], v[66:67] op_sel_hi:[1,0,1]
	v_lshlrev_b32_e32 v130, 16, v154
	v_and_b32_e32 v131, 0xffff0000, v154
	v_pk_fma_f32 v[68:69], v[132:133], s[18:19], v[68:69] op_sel_hi:[1,0,1]
	v_lshlrev_b32_e32 v132, 16, v155
	v_and_b32_e32 v133, 0xffff0000, v155
	v_pk_fma_f32 v[54:55], v[130:131], s[18:19], v[54:55] op_sel_hi:[1,0,1]
	v_lshlrev_b32_e32 v130, 16, v156
	v_and_b32_e32 v131, 0xffff0000, v156
	v_pk_fma_f32 v[56:57], v[132:133], s[18:19], v[56:57] op_sel_hi:[1,0,1]
	v_lshlrev_b32_e32 v132, 16, v157
	v_and_b32_e32 v133, 0xffff0000, v157
	v_pk_fma_f32 v[46:47], v[130:131], s[18:19], v[46:47] op_sel_hi:[1,0,1]
	v_lshlrev_b32_e32 v130, 16, v158
	v_and_b32_e32 v131, 0xffff0000, v158
	v_pk_fma_f32 v[48:49], v[132:133], s[18:19], v[48:49] op_sel_hi:[1,0,1]
	v_lshlrev_b32_e32 v132, 16, v159
	v_and_b32_e32 v133, 0xffff0000, v159
	v_pk_fma_f32 v[130:131], v[130:131], s[18:19], v[50:51] op_sel_hi:[1,0,1]
	v_lshlrev_b32_e32 v50, 16, v160
	v_and_b32_e32 v51, 0xffff0000, v160
	v_pk_fma_f32 v[132:133], v[132:133], s[18:19], v[52:53] op_sel_hi:[1,0,1]
	v_lshlrev_b32_e32 v52, 16, v161
	v_and_b32_e32 v53, 0xffff0000, v161
	v_pk_fma_f32 v[134:135], v[50:51], s[18:19], v[42:43] op_sel_hi:[1,0,1]
	v_lshlrev_b32_e32 v42, 16, v168
	v_and_b32_e32 v43, 0xffff0000, v168
	v_pk_fma_f32 v[136:137], v[52:53], s[18:19], v[44:45] op_sel_hi:[1,0,1]
	v_lshlrev_b32_e32 v44, 16, v169
	v_and_b32_e32 v45, 0xffff0000, v169
	v_pk_fma_f32 v[34:35], v[42:43], s[18:19], v[34:35] op_sel_hi:[1,0,1]
	v_lshlrev_b32_e32 v42, 16, v170
	v_and_b32_e32 v43, 0xffff0000, v170
	v_pk_fma_f32 v[36:37], v[44:45], s[18:19], v[36:37] op_sel_hi:[1,0,1]
	v_lshlrev_b32_e32 v44, 16, v171
	v_and_b32_e32 v45, 0xffff0000, v171
	v_pk_fma_f32 v[22:23], v[42:43], s[18:19], v[22:23] op_sel_hi:[1,0,1]
	v_lshlrev_b32_e32 v42, 16, v140
	v_and_b32_e32 v43, 0xffff0000, v140
	v_pk_fma_f32 v[110:111], v[138:139], s[18:19], v[110:111] op_sel_hi:[1,0,1]
	v_pk_fma_f32 v[24:25], v[44:45], s[18:19], v[24:25] op_sel_hi:[1,0,1]
	v_lshlrev_b32_e32 v44, 16, v141
	v_and_b32_e32 v45, 0xffff0000, v141
	v_pk_fma_f32 v[138:139], v[42:43], s[18:19], v[30:31] op_sel_hi:[1,0,1]
	v_lshlrev_b32_e32 v30, 16, v142
	v_and_b32_e32 v31, 0xffff0000, v142
	v_pk_fma_f32 v[140:141], v[44:45], s[18:19], v[32:33] op_sel_hi:[1,0,1]
	v_lshlrev_b32_e32 v32, 16, v143
	v_and_b32_e32 v33, 0xffff0000, v143
	v_pk_fma_f32 v[142:143], v[30:31], s[18:19], v[18:19] op_sel_hi:[1,0,1]
	v_lshlrev_b32_e32 v18, 16, v146
	v_and_b32_e32 v19, 0xffff0000, v146
	v_pk_fma_f32 v[144:145], v[32:33], s[18:19], v[20:21] op_sel_hi:[1,0,1]
	v_lshlrev_b32_e32 v20, 16, v147
	v_and_b32_e32 v21, 0xffff0000, v147
	v_pk_fma_f32 v[6:7], v[18:19], s[18:19], v[6:7] op_sel_hi:[1,0,1]
	v_lshlrev_b32_e32 v18, 16, v148
	v_and_b32_e32 v19, 0xffff0000, v148
	v_pk_fma_f32 v[8:9], v[20:21], s[18:19], v[8:9] op_sel_hi:[1,0,1]
	v_lshlrev_b32_e32 v20, 16, v149
	v_and_b32_e32 v21, 0xffff0000, v149
	v_pk_fma_f32 v[2:3], v[18:19], s[18:19], v[2:3] op_sel_hi:[1,0,1]
	v_lshlrev_b64 v[18:19], 2, v[162:163]
	v_pk_fma_f32 v[4:5], v[20:21], s[18:19], v[4:5] op_sel_hi:[1,0,1]
	v_lshl_add_u64 v[30:31], s[4:5], 0, v[18:19]
	v_lshl_add_u64 v[50:51], s[6:7], 0, v[18:19]
	global_load_dwordx4 v[146:149], v[30:31], off offset:16
	global_load_dwordx4 v[154:157], v[30:31], off
	global_load_dwordx4 v[150:153], v[50:51], off offset:16
	global_load_dwordx4 v[158:161], v[50:51], off
	global_load_dwordx4 v[18:21], v[30:31], off offset:528
	global_load_dwordx4 v[42:45], v[30:31], off offset:512
	s_nop 0
	global_load_dwordx4 v[30:33], v[50:51], off offset:528
	s_nop 0
	global_load_dwordx4 v[50:53], v[50:51], off offset:512
	v_cmp_lt_i32_e32 vcc, v165, v167
	v_xor_b32_e32 v168, 32, v219
	v_mov_b32_e32 v169, v92
	v_cndmask_b32_e32 v165, v219, v165, vcc
	v_cmp_lt_i32_e32 vcc, v168, v167
	v_mov_b32_e32 v170, v90
	v_mov_b32_e32 v171, v93
	v_cndmask_b32_e32 v167, v219, v168, vcc
	v_mov_b32_e32 v168, v91
	v_pk_add_f32 v[168:169], v[168:169], v[170:171]
	v_mov_b32_e32 v170, v95
	v_mov_b32_e32 v171, v96
	v_mov_b32_e32 v173, v97
	v_pk_add_f32 v[170:171], v[170:171], v[172:173]
	v_add_f32_e32 v168, v168, v169
	v_pk_add_f32 v[170:171], v[170:171], v[170:171] op_sel_hi:[0,1]
	v_add_f32_e32 v169, 0, v168
	v_add_f32_e32 v173, v10, v11
	v_add_f32_e32 v175, v12, v13
	v_mov_b32_e32 v172, v14
	v_mov_b32_e32 v174, v15
	v_mov_b32_e32 v170, v16
	v_mov_b32_e32 v168, v17
	v_pk_add_f32 v[172:173], v[172:173], v[174:175]
	v_pk_add_f32 v[168:169], v[170:171], v[168:169]
	v_lshlrev_b32_e32 v165, 2, v165
	v_pk_add_f32 v[168:169], v[172:173], v[168:169]
	v_lshlrev_b32_e32 v167, 2, v167
	v_add_f32_e32 v168, v168, v169
	v_mov_b32_e32 v169, v168
	s_nop 1
	v_permlane16_swap_b32 v169, v168
	s_lshl_b32 s0, s12, 3
	s_add_i32 s0, s0, 0
	v_cmp_gt_u32_e32 vcc, 16, v166
	v_add_f32_e32 v168, v168, v169
	v_mov_b32_e32 v169, v168
	s_nop 1
	v_permlane32_swap_b32 v169, v168
	v_add_f32_e32 v169, v168, v169
	v_fmamk_f32 v170, v169, 0xbc800000, v93
	v_fmamk_f32 v172, v169, 0xbc800000, v91
	v_fmamk_f32 v168, v169, 0xbc800000, v92
	v_fmamk_f32 v171, v169, 0xbc800000, v90
	v_mul_f32_e32 v172, v172, v172
	v_mul_f32_e32 v170, v170, v170
	v_fmac_f32_e32 v172, v171, v171
	v_fmac_f32_e32 v170, v168, v168
	v_fmamk_f32 v171, v169, 0xbc800000, v97
	v_fmamk_f32 v173, v169, 0xbc800000, v95
	v_add_f32_e32 v168, v172, v170
	v_fmamk_f32 v170, v169, 0xbc800000, v96
	v_fmamk_f32 v172, v169, 0xbc800000, v94
	v_mul_f32_e32 v173, v173, v173
	v_mul_f32_e32 v171, v171, v171
	v_fmac_f32_e32 v173, v172, v172
	v_fmac_f32_e32 v171, v170, v170
	v_add_f32_e32 v170, v173, v171
	v_fmamk_f32 v171, v169, 0xbc800000, v13
	v_fmamk_f32 v173, v169, 0xbc800000, v11
	v_add_f32_e32 v168, v168, v170
	v_fmamk_f32 v170, v169, 0xbc800000, v12
	v_fmamk_f32 v172, v169, 0xbc800000, v10
	v_mul_f32_e32 v173, v173, v173
	v_mul_f32_e32 v171, v171, v171
	v_fmac_f32_e32 v173, v172, v172
	v_fmac_f32_e32 v171, v170, v170
	v_add_f32_e32 v170, v173, v171
	v_fmamk_f32 v171, v169, 0xbc800000, v17
	v_fmamk_f32 v173, v169, 0xbc800000, v15
	v_add_f32_e32 v168, v170, v168
	v_fmamk_f32 v170, v169, 0xbc800000, v16
	v_fmamk_f32 v172, v169, 0xbc800000, v14
	v_mul_f32_e32 v173, v173, v173
	v_mul_f32_e32 v171, v171, v171
	v_fmac_f32_e32 v173, v172, v172
	v_fmac_f32_e32 v171, v170, v170
	v_add_f32_e32 v170, v173, v171
	v_add_f32_e32 v168, v170, v168
	v_mov_b32_e32 v170, v168
	s_nop 1
	v_permlane16_swap_b32 v170, v168
	v_add_f32_e32 v170, v168, v170
	v_mov_b32_e32 v171, v170
	s_nop 1
	v_permlane32_swap_b32 v171, v170
	v_lshl_add_u32 v168, v1, 5, s0
	s_and_saveexec_b64 s[0:1], vcc
	v_readlane_b32 s38, v255, 28
	v_readlane_b32 s39, v255, 29
	v_readlane_b32 s97, v255, 33
	v_readlane_b32 s42, v255, 32
	s_cbranch_execz .LBB0_658
	v_mul_f32_e32 v172, 0x3c800000, v169
	v_add_f32_e32 v173, v170, v171
	ds_write_b64 v168, v[172:173]
.LBB0_658:
	s_or_b64 exec, exec, s[0:1]
	v_mov_b32_e32 v170, v103
	v_mov_b32_e32 v171, v104
	v_mov_b32_e32 v172, v102
	v_mov_b32_e32 v173, v105
	v_pk_add_f32 v[170:171], v[170:171], v[172:173]
	v_mov_b32_e32 v172, v107
	v_mov_b32_e32 v173, v108
	v_mov_b32_e32 v174, v106
	v_mov_b32_e32 v175, v109
	v_pk_add_f32 v[172:173], v[172:173], v[174:175]
	v_add_f32_e32 v169, v170, v171
	v_pk_add_f32 v[172:173], v[172:173], v[172:173] op_sel_hi:[0,1]
	v_add_f32_e32 v171, 0, v169
	v_add_f32_e32 v175, v26, v27
	v_add_f32_e32 v177, v28, v29
	v_mov_b32_e32 v174, v38
	v_mov_b32_e32 v176, v39
	v_mov_b32_e32 v172, v40
	v_mov_b32_e32 v170, v41
	v_pk_add_f32 v[174:175], v[174:175], v[176:177]
	v_pk_add_f32 v[170:171], v[172:173], v[170:171]
	s_nop 0
	v_pk_add_f32 v[170:171], v[174:175], v[170:171]
	s_nop 0
	v_add_f32_e32 v169, v170, v171
	v_mov_b32_e32 v170, v169
	s_nop 1
	v_permlane16_swap_b32 v170, v169
	v_add_f32_e32 v169, v169, v170
	v_mov_b32_e32 v170, v169
	s_nop 1
	v_permlane32_swap_b32 v170, v169
	v_add_f32_e32 v169, v169, v170
	v_fmamk_f32 v171, v169, 0xbc800000, v105
	v_fmamk_f32 v173, v169, 0xbc800000, v103
	v_fmamk_f32 v170, v169, 0xbc800000, v104
	v_fmamk_f32 v172, v169, 0xbc800000, v102
	v_mul_f32_e32 v173, v173, v173
	v_mul_f32_e32 v171, v171, v171
	v_fmac_f32_e32 v173, v172, v172
	v_fmac_f32_e32 v171, v170, v170
	v_fmamk_f32 v172, v169, 0xbc800000, v109
	v_fmamk_f32 v174, v169, 0xbc800000, v107
	v_add_f32_e32 v170, v173, v171
	v_fmamk_f32 v171, v169, 0xbc800000, v108
	v_fmamk_f32 v173, v169, 0xbc800000, v106
	v_mul_f32_e32 v174, v174, v174
	v_mul_f32_e32 v172, v172, v172
	v_fmac_f32_e32 v174, v173, v173
	v_fmac_f32_e32 v172, v171, v171
	v_add_f32_e32 v171, v174, v172
	v_fmamk_f32 v172, v169, 0xbc800000, v29
	v_fmamk_f32 v174, v169, 0xbc800000, v27
	v_add_f32_e32 v170, v170, v171
	v_fmamk_f32 v171, v169, 0xbc800000, v28
	v_fmamk_f32 v173, v169, 0xbc800000, v26
	v_mul_f32_e32 v174, v174, v174
	v_mul_f32_e32 v172, v172, v172
	v_fmac_f32_e32 v174, v173, v173
	v_fmac_f32_e32 v172, v171, v171
	v_add_f32_e32 v171, v174, v172
	v_fmamk_f32 v172, v169, 0xbc800000, v41
	v_fmamk_f32 v174, v169, 0xbc800000, v39
	v_add_f32_e32 v170, v171, v170
	v_fmamk_f32 v171, v169, 0xbc800000, v40
	v_fmamk_f32 v173, v169, 0xbc800000, v38
	v_mul_f32_e32 v174, v174, v174
	v_mul_f32_e32 v172, v172, v172
	v_fmac_f32_e32 v174, v173, v173
	v_fmac_f32_e32 v172, v171, v171
	v_add_f32_e32 v171, v174, v172
	v_add_f32_e32 v170, v171, v170
	v_mov_b32_e32 v171, v170
	s_nop 1
	v_permlane16_swap_b32 v171, v170
	v_add_f32_e32 v170, v170, v171
	v_mov_b32_e32 v171, v170
	s_nop 1
	v_permlane32_swap_b32 v171, v170
	s_and_saveexec_b64 s[0:1], vcc
	v_readlane_b32 s44, v255, 30
	v_readlane_b32 s45, v255, 31
	s_cbranch_execz .LBB0_660
	v_mul_f32_e32 v172, 0x3c800000, v169
	v_add_f32_e32 v173, v170, v171
	ds_write_b64 v168, v[172:173] offset:512
.LBB0_660:
	s_or_b64 exec, exec, s[0:1]
	v_mov_b32_e32 v170, v115
	v_mov_b32_e32 v171, v116
	v_mov_b32_e32 v172, v114
	v_mov_b32_e32 v173, v117
	v_pk_add_f32 v[170:171], v[170:171], v[172:173]
	v_mov_b32_e32 v172, v119
	v_mov_b32_e32 v173, v120
	v_mov_b32_e32 v174, v118
	v_mov_b32_e32 v175, v121
	v_pk_add_f32 v[172:173], v[172:173], v[174:175]
	v_add_f32_e32 v169, v170, v171
	v_pk_add_f32 v[172:173], v[172:173], v[172:173] op_sel_hi:[0,1]
	v_add_f32_e32 v171, 0, v169
	v_add_f32_e32 v175, v58, v59
	v_add_f32_e32 v177, v60, v61
	v_mov_b32_e32 v174, v62
	v_mov_b32_e32 v176, v63
	v_mov_b32_e32 v172, v64
	v_mov_b32_e32 v170, v65
	v_pk_add_f32 v[174:175], v[174:175], v[176:177]
	v_pk_add_f32 v[170:171], v[172:173], v[170:171]
	s_nop 0
	v_pk_add_f32 v[170:171], v[174:175], v[170:171]
	s_nop 0
	v_add_f32_e32 v169, v170, v171
	v_mov_b32_e32 v170, v169
	s_nop 1
	v_permlane16_swap_b32 v170, v169
	v_add_f32_e32 v169, v169, v170
	v_mov_b32_e32 v170, v169
	s_nop 1
	v_permlane32_swap_b32 v170, v169
	v_add_f32_e32 v169, v169, v170
	v_fmamk_f32 v171, v169, 0xbc800000, v117
	v_fmamk_f32 v173, v169, 0xbc800000, v115
	v_fmamk_f32 v170, v169, 0xbc800000, v116
	v_fmamk_f32 v172, v169, 0xbc800000, v114
	v_mul_f32_e32 v173, v173, v173
	v_mul_f32_e32 v171, v171, v171
	v_fmac_f32_e32 v173, v172, v172
	v_fmac_f32_e32 v171, v170, v170
	v_fmamk_f32 v172, v169, 0xbc800000, v121
	v_fmamk_f32 v174, v169, 0xbc800000, v119
	v_add_f32_e32 v170, v173, v171
	v_fmamk_f32 v171, v169, 0xbc800000, v120
	v_fmamk_f32 v173, v169, 0xbc800000, v118
	v_mul_f32_e32 v174, v174, v174
	v_mul_f32_e32 v172, v172, v172
	v_fmac_f32_e32 v174, v173, v173
	v_fmac_f32_e32 v172, v171, v171
	v_add_f32_e32 v171, v174, v172
	v_fmamk_f32 v172, v169, 0xbc800000, v61
	v_fmamk_f32 v174, v169, 0xbc800000, v59
	v_add_f32_e32 v170, v170, v171
	v_fmamk_f32 v171, v169, 0xbc800000, v60
	v_fmamk_f32 v173, v169, 0xbc800000, v58
	v_mul_f32_e32 v174, v174, v174
	v_mul_f32_e32 v172, v172, v172
	v_fmac_f32_e32 v174, v173, v173
	v_fmac_f32_e32 v172, v171, v171
	v_add_f32_e32 v171, v174, v172
	v_fmamk_f32 v172, v169, 0xbc800000, v65
	v_fmamk_f32 v174, v169, 0xbc800000, v63
	v_add_f32_e32 v170, v171, v170
	v_fmamk_f32 v171, v169, 0xbc800000, v64
	v_fmamk_f32 v173, v169, 0xbc800000, v62
	v_mul_f32_e32 v174, v174, v174
	v_mul_f32_e32 v172, v172, v172
	v_fmac_f32_e32 v174, v173, v173
	v_fmac_f32_e32 v172, v171, v171
	v_add_f32_e32 v171, v174, v172
	v_add_f32_e32 v170, v171, v170
	v_mov_b32_e32 v171, v170
	s_nop 1
	v_permlane16_swap_b32 v171, v170
	v_add_f32_e32 v170, v170, v171
	v_mov_b32_e32 v171, v170
	s_nop 1
	v_permlane32_swap_b32 v171, v170
	s_and_saveexec_b64 s[0:1], vcc
	s_cbranch_execz .LBB0_662
	v_mul_f32_e32 v172, 0x3c800000, v169
	v_add_f32_e32 v173, v170, v171
	ds_write_b64 v168, v[172:173] offset:1024
.LBB0_662:
	s_or_b64 exec, exec, s[0:1]
	v_mov_b32_e32 v170, v123
	v_mov_b32_e32 v171, v124
	v_mov_b32_e32 v172, v122
	v_mov_b32_e32 v173, v125
	v_pk_add_f32 v[170:171], v[170:171], v[172:173]
	v_mov_b32_e32 v172, v127
	v_mov_b32_e32 v173, v128
	v_mov_b32_e32 v174, v126
	v_mov_b32_e32 v175, v129
	v_pk_add_f32 v[172:173], v[172:173], v[174:175]
	v_add_f32_e32 v169, v170, v171
	v_pk_add_f32 v[172:173], v[172:173], v[172:173] op_sel_hi:[0,1]
	v_add_f32_e32 v171, 0, v169
	v_add_f32_e32 v175, v74, v75
	v_add_f32_e32 v177, v76, v77
	v_mov_b32_e32 v174, v78
	v_mov_b32_e32 v176, v79
	v_mov_b32_e32 v172, v80
	v_mov_b32_e32 v170, v81
	v_pk_add_f32 v[174:175], v[174:175], v[176:177]
	v_pk_add_f32 v[170:171], v[172:173], v[170:171]
	s_nop 0
	v_pk_add_f32 v[170:171], v[174:175], v[170:171]
	s_nop 0
	v_add_f32_e32 v169, v170, v171
	v_mov_b32_e32 v170, v169
	s_nop 1
	v_permlane16_swap_b32 v170, v169
	v_add_f32_e32 v169, v169, v170
	v_mov_b32_e32 v170, v169
	s_nop 1
	v_permlane32_swap_b32 v170, v169
	v_add_f32_e32 v169, v169, v170
	v_fmamk_f32 v171, v169, 0xbc800000, v125
	v_fmamk_f32 v173, v169, 0xbc800000, v123
	v_fmamk_f32 v170, v169, 0xbc800000, v124
	v_fmamk_f32 v172, v169, 0xbc800000, v122
	v_mul_f32_e32 v173, v173, v173
	v_mul_f32_e32 v171, v171, v171
	v_fmac_f32_e32 v173, v172, v172
	v_fmac_f32_e32 v171, v170, v170
	v_fmamk_f32 v172, v169, 0xbc800000, v129
	v_fmamk_f32 v174, v169, 0xbc800000, v127
	v_add_f32_e32 v170, v173, v171
	v_fmamk_f32 v171, v169, 0xbc800000, v128
	v_fmamk_f32 v173, v169, 0xbc800000, v126
	v_mul_f32_e32 v174, v174, v174
	v_mul_f32_e32 v172, v172, v172
	v_fmac_f32_e32 v174, v173, v173
	v_fmac_f32_e32 v172, v171, v171
	v_add_f32_e32 v171, v174, v172
	v_fmamk_f32 v172, v169, 0xbc800000, v77
	v_fmamk_f32 v174, v169, 0xbc800000, v75
	v_add_f32_e32 v170, v170, v171
	v_fmamk_f32 v171, v169, 0xbc800000, v76
	v_fmamk_f32 v173, v169, 0xbc800000, v74
	v_mul_f32_e32 v174, v174, v174
	v_mul_f32_e32 v172, v172, v172
	v_fmac_f32_e32 v174, v173, v173
	v_fmac_f32_e32 v172, v171, v171
	v_add_f32_e32 v171, v174, v172
	v_fmamk_f32 v172, v169, 0xbc800000, v81
	v_fmamk_f32 v174, v169, 0xbc800000, v79
	v_add_f32_e32 v170, v171, v170
	v_fmamk_f32 v171, v169, 0xbc800000, v80
	v_fmamk_f32 v173, v169, 0xbc800000, v78
	v_mul_f32_e32 v174, v174, v174
	v_mul_f32_e32 v172, v172, v172
	v_fmac_f32_e32 v174, v173, v173
	v_fmac_f32_e32 v172, v171, v171
	v_add_f32_e32 v171, v174, v172
	v_add_f32_e32 v170, v171, v170
	v_mov_b32_e32 v171, v170
	s_nop 1
	v_permlane16_swap_b32 v171, v170
	v_add_f32_e32 v170, v170, v171
	v_mov_b32_e32 v171, v170
	s_nop 1
	v_permlane32_swap_b32 v171, v170
	s_and_saveexec_b64 s[0:1], vcc
	s_cbranch_execz .LBB0_664
	v_mul_f32_e32 v172, 0x3c800000, v169
	v_add_f32_e32 v173, v170, v171
	ds_write_b64 v168, v[172:173] offset:1536
.LBB0_664:
	s_or_b64 exec, exec, s[0:1]
	v_mov_b32_e32 v170, v111
	v_mov_b32_e32 v171, v112
	v_mov_b32_e32 v172, v110
	v_mov_b32_e32 v173, v113
	v_pk_add_f32 v[170:171], v[170:171], v[172:173]
	v_mov_b32_e32 v172, v99
	v_mov_b32_e32 v173, v100
	v_mov_b32_e32 v174, v98
	v_mov_b32_e32 v175, v101
	v_pk_add_f32 v[172:173], v[172:173], v[174:175]
	v_add_f32_e32 v169, v170, v171
	v_pk_add_f32 v[172:173], v[172:173], v[172:173] op_sel_hi:[0,1]
	v_add_f32_e32 v171, 0, v169
	v_add_f32_e32 v175, v86, v87
	v_add_f32_e32 v177, v88, v89
	v_mov_b32_e32 v174, v70
	v_mov_b32_e32 v176, v71
	v_mov_b32_e32 v172, v72
	v_mov_b32_e32 v170, v73
	v_pk_add_f32 v[174:175], v[174:175], v[176:177]
	v_pk_add_f32 v[170:171], v[172:173], v[170:171]
	s_nop 0
	v_pk_add_f32 v[170:171], v[174:175], v[170:171]
	s_nop 0
	v_add_f32_e32 v169, v170, v171
	v_mov_b32_e32 v170, v169
	s_nop 1
	v_permlane16_swap_b32 v170, v169
	v_add_f32_e32 v169, v169, v170
	v_mov_b32_e32 v170, v169
	s_nop 1
	v_permlane32_swap_b32 v170, v169
	v_add_f32_e32 v169, v169, v170
	v_fmamk_f32 v171, v169, 0xbc800000, v113
	v_fmamk_f32 v173, v169, 0xbc800000, v111
	v_fmamk_f32 v170, v169, 0xbc800000, v112
	v_fmamk_f32 v172, v169, 0xbc800000, v110
	v_mul_f32_e32 v173, v173, v173
	v_mul_f32_e32 v171, v171, v171
	v_fmac_f32_e32 v173, v172, v172
	v_fmac_f32_e32 v171, v170, v170
	v_fmamk_f32 v172, v169, 0xbc800000, v101
	v_fmamk_f32 v174, v169, 0xbc800000, v99
	v_add_f32_e32 v170, v173, v171
	v_fmamk_f32 v171, v169, 0xbc800000, v100
	v_fmamk_f32 v173, v169, 0xbc800000, v98
	v_mul_f32_e32 v174, v174, v174
	v_mul_f32_e32 v172, v172, v172
	v_fmac_f32_e32 v174, v173, v173
	v_fmac_f32_e32 v172, v171, v171
	v_add_f32_e32 v171, v174, v172
	v_fmamk_f32 v172, v169, 0xbc800000, v89
	v_fmamk_f32 v174, v169, 0xbc800000, v87
	v_add_f32_e32 v170, v170, v171
	v_fmamk_f32 v171, v169, 0xbc800000, v88
	v_fmamk_f32 v173, v169, 0xbc800000, v86
	v_mul_f32_e32 v174, v174, v174
	v_mul_f32_e32 v172, v172, v172
	v_fmac_f32_e32 v174, v173, v173
	v_fmac_f32_e32 v172, v171, v171
	v_add_f32_e32 v171, v174, v172
	v_fmamk_f32 v172, v169, 0xbc800000, v73
	v_fmamk_f32 v174, v169, 0xbc800000, v71
	v_add_f32_e32 v170, v171, v170
	v_fmamk_f32 v171, v169, 0xbc800000, v72
	v_fmamk_f32 v173, v169, 0xbc800000, v70
	v_mul_f32_e32 v174, v174, v174
	v_mul_f32_e32 v172, v172, v172
	v_fmac_f32_e32 v174, v173, v173
	v_fmac_f32_e32 v172, v171, v171
	v_add_f32_e32 v171, v174, v172
	v_add_f32_e32 v170, v171, v170
	v_mov_b32_e32 v171, v170
	s_nop 1
	v_permlane16_swap_b32 v171, v170
	v_add_f32_e32 v170, v170, v171
	v_mov_b32_e32 v171, v170
	s_nop 1
	v_permlane32_swap_b32 v171, v170
	s_and_saveexec_b64 s[0:1], vcc
	s_cbranch_execz .LBB0_666
	v_mul_f32_e32 v172, 0x3c800000, v169
	v_add_f32_e32 v173, v170, v171
	ds_write_b64 v168, v[172:173] offset:4096
.LBB0_666:
	s_or_b64 exec, exec, s[0:1]
	v_mov_b32_e32 v170, v83
	v_mov_b32_e32 v171, v84
	v_mov_b32_e32 v172, v82
	v_mov_b32_e32 v173, v85
	v_pk_add_f32 v[170:171], v[170:171], v[172:173]
	v_mov_b32_e32 v172, v67
	v_mov_b32_e32 v173, v68
	v_mov_b32_e32 v174, v66
	v_mov_b32_e32 v175, v69
	v_pk_add_f32 v[172:173], v[172:173], v[174:175]
	v_add_f32_e32 v169, v170, v171
	v_pk_add_f32 v[172:173], v[172:173], v[172:173] op_sel_hi:[0,1]
	v_add_f32_e32 v171, 0, v169
	v_add_f32_e32 v175, v54, v55
	v_add_f32_e32 v177, v56, v57
	v_mov_b32_e32 v174, v46
	v_mov_b32_e32 v176, v47
	v_mov_b32_e32 v172, v48
	v_mov_b32_e32 v170, v49
	v_pk_add_f32 v[174:175], v[174:175], v[176:177]
	v_pk_add_f32 v[170:171], v[172:173], v[170:171]
	s_nop 0
	v_pk_add_f32 v[170:171], v[174:175], v[170:171]
	s_nop 0
	v_add_f32_e32 v169, v170, v171
	v_mov_b32_e32 v170, v169
	s_nop 1
	v_permlane16_swap_b32 v170, v169
	v_add_f32_e32 v169, v169, v170
	v_mov_b32_e32 v170, v169
	s_nop 1
	v_permlane32_swap_b32 v170, v169
	v_add_f32_e32 v169, v169, v170
	v_fmamk_f32 v171, v169, 0xbc800000, v85
	v_fmamk_f32 v173, v169, 0xbc800000, v83
	v_fmamk_f32 v170, v169, 0xbc800000, v84
	v_fmamk_f32 v172, v169, 0xbc800000, v82
	v_mul_f32_e32 v173, v173, v173
	v_mul_f32_e32 v171, v171, v171
	v_fmac_f32_e32 v173, v172, v172
	v_fmac_f32_e32 v171, v170, v170
	v_fmamk_f32 v172, v169, 0xbc800000, v69
	v_fmamk_f32 v174, v169, 0xbc800000, v67
	v_add_f32_e32 v170, v173, v171
	v_fmamk_f32 v171, v169, 0xbc800000, v68
	v_fmamk_f32 v173, v169, 0xbc800000, v66
	v_mul_f32_e32 v174, v174, v174
	v_mul_f32_e32 v172, v172, v172
	v_fmac_f32_e32 v174, v173, v173
	v_fmac_f32_e32 v172, v171, v171
	v_add_f32_e32 v171, v174, v172
	v_fmamk_f32 v172, v169, 0xbc800000, v57
	v_fmamk_f32 v174, v169, 0xbc800000, v55
	v_add_f32_e32 v170, v170, v171
	v_fmamk_f32 v171, v169, 0xbc800000, v56
	v_fmamk_f32 v173, v169, 0xbc800000, v54
	v_mul_f32_e32 v174, v174, v174
	v_mul_f32_e32 v172, v172, v172
	v_fmac_f32_e32 v174, v173, v173
	v_fmac_f32_e32 v172, v171, v171
	v_add_f32_e32 v171, v174, v172
	v_fmamk_f32 v172, v169, 0xbc800000, v49
	v_fmamk_f32 v174, v169, 0xbc800000, v47
	v_add_f32_e32 v170, v171, v170
	v_fmamk_f32 v171, v169, 0xbc800000, v48
	v_fmamk_f32 v173, v169, 0xbc800000, v46
	v_mul_f32_e32 v174, v174, v174
	v_mul_f32_e32 v172, v172, v172
	v_fmac_f32_e32 v174, v173, v173
	v_fmac_f32_e32 v172, v171, v171
	v_add_f32_e32 v171, v174, v172
	v_add_f32_e32 v170, v171, v170
	v_mov_b32_e32 v171, v170
	s_nop 1
	v_permlane16_swap_b32 v171, v170
	v_add_f32_e32 v170, v170, v171
	v_mov_b32_e32 v171, v170
	s_nop 1
	v_permlane32_swap_b32 v171, v170
	s_and_saveexec_b64 s[0:1], vcc
	s_cbranch_execz .LBB0_668
	v_mul_f32_e32 v172, 0x3c800000, v169
	v_add_f32_e32 v173, v170, v171
	ds_write_b64 v168, v[172:173] offset:4608
.LBB0_668:
	s_or_b64 exec, exec, s[0:1]
	v_mov_b32_e32 v170, v131
	v_mov_b32_e32 v171, v132
	v_mov_b32_e32 v172, v130
	v_mov_b32_e32 v173, v133
	v_pk_add_f32 v[170:171], v[170:171], v[172:173]
	v_mov_b32_e32 v172, v135
	v_mov_b32_e32 v173, v136
	v_mov_b32_e32 v174, v134
	v_mov_b32_e32 v175, v137
	v_pk_add_f32 v[172:173], v[172:173], v[174:175]
	v_add_f32_e32 v169, v170, v171
	v_pk_add_f32 v[172:173], v[172:173], v[172:173] op_sel_hi:[0,1]
	v_add_f32_e32 v171, 0, v169
	v_add_f32_e32 v175, v34, v35
	v_add_f32_e32 v177, v36, v37
	v_mov_b32_e32 v174, v22
	v_mov_b32_e32 v176, v23
	v_mov_b32_e32 v172, v24
	v_mov_b32_e32 v170, v25
	v_pk_add_f32 v[174:175], v[174:175], v[176:177]
	v_pk_add_f32 v[170:171], v[172:173], v[170:171]
	s_nop 0
	v_pk_add_f32 v[170:171], v[174:175], v[170:171]
	s_nop 0
	v_add_f32_e32 v169, v170, v171
	v_mov_b32_e32 v170, v169
	s_nop 1
	v_permlane16_swap_b32 v170, v169
	v_add_f32_e32 v169, v169, v170
	v_mov_b32_e32 v170, v169
	s_nop 1
	v_permlane32_swap_b32 v170, v169
	v_add_f32_e32 v169, v169, v170
	v_fmamk_f32 v171, v169, 0xbc800000, v133
	v_fmamk_f32 v173, v169, 0xbc800000, v131
	v_fmamk_f32 v170, v169, 0xbc800000, v132
	v_fmamk_f32 v172, v169, 0xbc800000, v130
	v_mul_f32_e32 v173, v173, v173
	v_mul_f32_e32 v171, v171, v171
	v_fmac_f32_e32 v173, v172, v172
	v_fmac_f32_e32 v171, v170, v170
	v_fmamk_f32 v172, v169, 0xbc800000, v137
	v_fmamk_f32 v174, v169, 0xbc800000, v135
	v_add_f32_e32 v170, v173, v171
	v_fmamk_f32 v171, v169, 0xbc800000, v136
	v_fmamk_f32 v173, v169, 0xbc800000, v134
	v_mul_f32_e32 v174, v174, v174
	v_mul_f32_e32 v172, v172, v172
	v_fmac_f32_e32 v174, v173, v173
	v_fmac_f32_e32 v172, v171, v171
	v_add_f32_e32 v171, v174, v172
	v_fmamk_f32 v172, v169, 0xbc800000, v37
	v_fmamk_f32 v174, v169, 0xbc800000, v35
	v_add_f32_e32 v170, v170, v171
	v_fmamk_f32 v171, v169, 0xbc800000, v36
	v_fmamk_f32 v173, v169, 0xbc800000, v34
	v_mul_f32_e32 v174, v174, v174
	v_mul_f32_e32 v172, v172, v172
	v_fmac_f32_e32 v174, v173, v173
	v_fmac_f32_e32 v172, v171, v171
	v_add_f32_e32 v171, v174, v172
	v_fmamk_f32 v172, v169, 0xbc800000, v25
	v_fmamk_f32 v174, v169, 0xbc800000, v23
	v_add_f32_e32 v170, v171, v170
	v_fmamk_f32 v171, v169, 0xbc800000, v24
	v_fmamk_f32 v173, v169, 0xbc800000, v22
	v_mul_f32_e32 v174, v174, v174
	v_mul_f32_e32 v172, v172, v172
	v_fmac_f32_e32 v174, v173, v173
	v_fmac_f32_e32 v172, v171, v171
	v_add_f32_e32 v171, v174, v172
	v_add_f32_e32 v170, v171, v170
	v_mov_b32_e32 v171, v170
	s_nop 1
	v_permlane16_swap_b32 v171, v170
	v_add_f32_e32 v170, v170, v171
	v_mov_b32_e32 v171, v170
	s_nop 1
	v_permlane32_swap_b32 v171, v170
	s_and_saveexec_b64 s[0:1], vcc
	s_cbranch_execz .LBB0_670
	v_mul_f32_e32 v172, 0x3c800000, v169
	v_add_f32_e32 v173, v170, v171
	ds_write_b64 v168, v[172:173] offset:5120
.LBB0_670:
	s_or_b64 exec, exec, s[0:1]
	v_mov_b32_e32 v170, v139
	v_mov_b32_e32 v171, v140
	v_mov_b32_e32 v172, v138
	v_mov_b32_e32 v173, v141
	v_pk_add_f32 v[170:171], v[170:171], v[172:173]
	v_mov_b32_e32 v172, v143
	v_mov_b32_e32 v173, v144
	v_mov_b32_e32 v174, v142
	v_mov_b32_e32 v175, v145
	v_pk_add_f32 v[172:173], v[172:173], v[174:175]
	v_add_f32_e32 v169, v170, v171
	v_pk_add_f32 v[172:173], v[172:173], v[172:173] op_sel_hi:[0,1]
	v_add_f32_e32 v171, 0, v169
	v_add_f32_e32 v175, v6, v7
	v_add_f32_e32 v177, v8, v9
	v_mov_b32_e32 v174, v2
	v_mov_b32_e32 v176, v3
	v_mov_b32_e32 v172, v4
	v_mov_b32_e32 v170, v5
	v_pk_add_f32 v[174:175], v[174:175], v[176:177]
	v_pk_add_f32 v[170:171], v[172:173], v[170:171]
	s_nop 0
	v_pk_add_f32 v[170:171], v[174:175], v[170:171]
	s_nop 0
	v_add_f32_e32 v169, v170, v171
	v_mov_b32_e32 v170, v169
	s_nop 1
	v_permlane16_swap_b32 v170, v169
	v_add_f32_e32 v169, v169, v170
	v_mov_b32_e32 v170, v169
	s_nop 1
	v_permlane32_swap_b32 v170, v169
	v_add_f32_e32 v169, v169, v170
	v_fmamk_f32 v171, v169, 0xbc800000, v141
	v_fmamk_f32 v173, v169, 0xbc800000, v139
	v_fmamk_f32 v170, v169, 0xbc800000, v140
	v_fmamk_f32 v172, v169, 0xbc800000, v138
	v_mul_f32_e32 v173, v173, v173
	v_mul_f32_e32 v171, v171, v171
	v_fmac_f32_e32 v173, v172, v172
	v_fmac_f32_e32 v171, v170, v170
	v_fmamk_f32 v172, v169, 0xbc800000, v145
	v_fmamk_f32 v174, v169, 0xbc800000, v143
	v_add_f32_e32 v170, v173, v171
	v_fmamk_f32 v171, v169, 0xbc800000, v144
	v_fmamk_f32 v173, v169, 0xbc800000, v142
	v_mul_f32_e32 v174, v174, v174
	v_mul_f32_e32 v172, v172, v172
	v_fmac_f32_e32 v174, v173, v173
	v_fmac_f32_e32 v172, v171, v171
	v_add_f32_e32 v171, v174, v172
	v_fmamk_f32 v172, v169, 0xbc800000, v9
	v_fmamk_f32 v174, v169, 0xbc800000, v7
	v_add_f32_e32 v170, v170, v171
	v_fmamk_f32 v171, v169, 0xbc800000, v8
	v_fmamk_f32 v173, v169, 0xbc800000, v6
	v_mul_f32_e32 v174, v174, v174
	v_mul_f32_e32 v172, v172, v172
	v_fmac_f32_e32 v174, v173, v173
	v_fmac_f32_e32 v172, v171, v171
	v_add_f32_e32 v171, v174, v172
	v_fmamk_f32 v172, v169, 0xbc800000, v5
	v_fmamk_f32 v174, v169, 0xbc800000, v3
	v_add_f32_e32 v170, v171, v170
	v_fmamk_f32 v171, v169, 0xbc800000, v4
	v_fmamk_f32 v173, v169, 0xbc800000, v2
	v_mul_f32_e32 v174, v174, v174
	v_mul_f32_e32 v172, v172, v172
	v_fmac_f32_e32 v174, v173, v173
	v_fmac_f32_e32 v172, v171, v171
	v_add_f32_e32 v171, v174, v172
	v_add_f32_e32 v170, v171, v170
	v_mov_b32_e32 v165, v170
	s_nop 1
	v_permlane16_swap_b32 v165, v170
	v_add_f32_e32 v165, v170, v165
	v_mov_b32_e32 v167, v165
	s_nop 1
	v_permlane32_swap_b32 v167, v165
	s_and_saveexec_b64 s[0:1], vcc
	s_cbranch_execz .LBB0_672
	v_mul_f32_e32 v170, 0x3c800000, v169
	v_add_f32_e32 v171, v165, v167
	ds_write_b64 v168, v[170:171] offset:5632

.LBB0_819:
	s_lshl_b32 s30, s25, 8
	s_add_i32 s1, s30, s46
	s_lshl_b32 s0, s10, 5
	v_or_b32_e32 v130, s1, v138
	s_lshl_b32 s1, s80, 8
	v_lshrrev_b32_e32 v131, 1, v166
	s_or_b32 s0, s1, s0
	v_and_or_b32 v164, v131, 24, s0
	v_ashrrev_i32_e32 v165, 31, v164
	v_ashrrev_i32_e32 v131, 31, v130
	v_lshl_add_u64 v[162:163], v[164:165], 1, s[34:35]
	v_lshlrev_b64 v[132:133], 12, v[130:131]
	v_lshl_add_u64 v[146:147], v[162:163], 0, v[132:133]
	v_or_b32_e32 v132, 16, v130
	v_ashrrev_i32_e32 v133, 31, v132
	v_lshlrev_b64 v[132:133], 12, v[132:133]
	v_lshl_add_u64 v[132:133], v[162:163], 0, v[132:133]
	s_barrier
	global_load_dwordx4 v[148:151], v[146:147], off
	global_load_dwordx4 v[152:155], v[146:147], off offset:256
	global_load_dwordx4 v[156:159], v[132:133], off
	global_load_dwordx4 v[170:173], v[132:133], off offset:256
	v_or_b32_e32 v132, 32, v130
	v_or_b32_e32 v130, 48, v130
	v_ashrrev_i32_e32 v133, 31, v132
	v_ashrrev_i32_e32 v131, 31, v130
	v_lshlrev_b64 v[132:133], 12, v[132:133]
	v_lshlrev_b64 v[130:131], 12, v[130:131]
	v_lshl_add_u64 v[132:133], v[162:163], 0, v[132:133]
	v_lshl_add_u64 v[130:131], v[162:163], 0, v[130:131]
	global_load_dwordx4 v[142:145], v[132:133], off
	global_load_dwordx4 v[138:141], v[132:133], off offset:256
	global_load_dwordx4 v[134:137], v[130:131], off
	s_nop 0
	global_load_dwordx4 v[130:133], v[130:131], off offset:256
	s_mov_b32 s18, 0x3fd744fd
	s_mov_b64 s[0:1], 0x80000
	v_and_b32_e32 v169, 64, v219
	v_xor_b32_e32 v167, 16, v219
	v_add_u32_e32 v169, 64, v169
	v_and_b32_e32 v168, 63, v166
	s_movk_i32 s95, 0x2000
	s_waitcnt vmcnt(0)
	s_nop 0
	v_lshlrev_b32_e32 v160, 16, v148
	v_and_b32_e32 v161, 0xffff0000, v148
	v_lshlrev_b32_e32 v148, 16, v149
	v_and_b32_e32 v149, 0xffff0000, v149
	v_pk_fma_f32 v[88:89], v[148:149], s[18:19], v[88:89] op_sel_hi:[1,0,1]
	v_lshlrev_b32_e32 v148, 16, v150
	v_and_b32_e32 v149, 0xffff0000, v150
	v_pk_fma_f32 v[94:95], v[148:149], s[18:19], v[94:95] op_sel_hi:[1,0,1]
	v_lshlrev_b32_e32 v148, 16, v152
	v_and_b32_e32 v149, 0xffff0000, v152
	v_pk_fma_f32 v[2:3], v[148:149], s[18:19], v[2:3] op_sel_hi:[1,0,1]
	v_lshlrev_b32_e32 v148, 16, v154
	v_and_b32_e32 v149, 0xffff0000, v154
	v_pk_fma_f32 v[6:7], v[148:149], s[18:19], v[6:7] op_sel_hi:[1,0,1]
	v_lshlrev_b32_e32 v148, 16, v156
	v_and_b32_e32 v149, 0xffff0000, v156
	v_pk_fma_f32 v[98:99], v[148:149], s[18:19], v[98:99] op_sel_hi:[1,0,1]
	v_lshlrev_b32_e32 v148, 16, v158
	v_and_b32_e32 v149, 0xffff0000, v158
	v_pk_fma_f32 v[102:103], v[148:149], s[18:19], v[102:103] op_sel_hi:[1,0,1]
	v_lshlrev_b32_e32 v148, 16, v170
	v_and_b32_e32 v149, 0xffff0000, v170
	v_pk_fma_f32 v[10:11], v[148:149], s[18:19], v[10:11] op_sel_hi:[1,0,1]
	v_lshlrev_b32_e32 v148, 16, v172
	v_and_b32_e32 v149, 0xffff0000, v172
	v_pk_fma_f32 v[14:15], v[148:149], s[18:19], v[14:15] op_sel_hi:[1,0,1]
	v_lshlrev_b32_e32 v148, 16, v142
	v_and_b32_e32 v149, 0xffff0000, v142
	v_lshlrev_b32_e32 v142, 16, v143
	v_and_b32_e32 v143, 0xffff0000, v143
	v_pk_fma_f32 v[116:117], v[142:143], s[18:19], v[116:117] op_sel_hi:[1,0,1]
	v_lshlrev_b32_e32 v142, 16, v144
	v_and_b32_e32 v143, 0xffff0000, v144
	v_pk_fma_f32 v[122:123], v[142:143], s[18:19], v[122:123] op_sel_hi:[1,0,1]
	v_lshlrev_b32_e32 v142, 16, v138
	v_and_b32_e32 v143, 0xffff0000, v138
	v_lshlrev_b32_e32 v138, 16, v139
	v_and_b32_e32 v139, 0xffff0000, v139
	v_pk_fma_f32 v[24:25], v[138:139], s[18:19], v[24:25] op_sel_hi:[1,0,1]
	v_lshlrev_b32_e32 v138, 16, v140
	v_and_b32_e32 v139, 0xffff0000, v140
	v_lshlrev_b32_e32 v150, 16, v151
	v_and_b32_e32 v151, 0xffff0000, v151
	v_pk_fma_f32 v[18:19], v[138:139], s[18:19], v[18:19] op_sel_hi:[1,0,1]
	v_lshlrev_b32_e32 v138, 16, v134
	v_and_b32_e32 v139, 0xffff0000, v134
	v_lshlrev_b32_e32 v134, 16, v135
	v_and_b32_e32 v135, 0xffff0000, v135
	v_pk_fma_f32 v[96:97], v[150:151], s[18:19], v[96:97] op_sel_hi:[1,0,1]
	v_lshlrev_b32_e32 v150, 16, v153
	v_and_b32_e32 v151, 0xffff0000, v153
	v_pk_fma_f32 v[128:129], v[134:135], s[18:19], v[128:129] op_sel_hi:[1,0,1]
	v_lshlrev_b32_e32 v134, 16, v136
	v_and_b32_e32 v135, 0xffff0000, v136
	v_pk_fma_f32 v[4:5], v[150:151], s[18:19], v[4:5] op_sel_hi:[1,0,1]
	v_lshlrev_b32_e32 v150, 16, v155
	v_and_b32_e32 v151, 0xffff0000, v155
	v_pk_fma_f32 v[118:119], v[134:135], s[18:19], v[118:119] op_sel_hi:[1,0,1]
	v_lshlrev_b32_e32 v134, 16, v130
	v_and_b32_e32 v135, 0xffff0000, v130
	v_lshlrev_b32_e32 v130, 16, v131
	v_and_b32_e32 v131, 0xffff0000, v131
	v_pk_fma_f32 v[8:9], v[150:151], s[18:19], v[8:9] op_sel_hi:[1,0,1]
	v_lshlrev_b32_e32 v150, 16, v157
	v_and_b32_e32 v151, 0xffff0000, v157
	v_pk_fma_f32 v[32:33], v[130:131], s[18:19], v[32:33] op_sel_hi:[1,0,1]
	v_pk_fma_f32 v[30:31], v[134:135], s[18:19], v[30:31] op_sel_hi:[1,0,1]
	v_lshlrev_b32_e32 v130, 16, v132
	v_and_b32_e32 v131, 0xffff0000, v132
	v_lshl_add_u64 v[134:135], v[146:147], 0, s[0:1]
	s_mov_b32 s0, 0x80000
	v_pk_fma_f32 v[100:101], v[150:151], s[18:19], v[100:101] op_sel_hi:[1,0,1]
	v_lshlrev_b32_e32 v150, 16, v159
	v_and_b32_e32 v151, 0xffff0000, v159
	v_pk_fma_f32 v[26:27], v[130:131], s[18:19], v[26:27] op_sel_hi:[1,0,1]
	v_add_co_u32_e32 v130, vcc, s0, v146
	s_mov_b64 s[0:1], 0x90000
	v_pk_fma_f32 v[104:105], v[150:151], s[18:19], v[104:105] op_sel_hi:[1,0,1]
	v_lshlrev_b32_e32 v150, 16, v171
	v_and_b32_e32 v151, 0xffff0000, v171
	v_pk_fma_f32 v[22:23], v[142:143], s[18:19], v[22:23] op_sel_hi:[1,0,1]
	v_addc_co_u32_e32 v131, vcc, 0, v147, vcc
	v_lshl_add_u64 v[142:143], v[146:147], 0, s[0:1]
	s_mov_b32 s0, 0x90000
	v_pk_fma_f32 v[12:13], v[150:151], s[18:19], v[12:13] op_sel_hi:[1,0,1]
	v_lshlrev_b32_e32 v150, 16, v173
	v_and_b32_e32 v151, 0xffff0000, v173
	v_lshlrev_b32_e32 v144, 16, v145
	v_and_b32_e32 v145, 0xffff0000, v145
	v_lshlrev_b32_e32 v140, 16, v141
	v_and_b32_e32 v141, 0xffff0000, v141
	v_pk_fma_f32 v[126:127], v[138:139], s[18:19], v[126:127] op_sel_hi:[1,0,1]
	v_lshlrev_b32_e32 v136, 16, v137
	v_and_b32_e32 v137, 0xffff0000, v137
	v_lshlrev_b32_e32 v132, 16, v133
	v_and_b32_e32 v133, 0xffff0000, v133
	v_add_co_u32_e32 v138, vcc, s0, v146
	v_pk_fma_f32 v[86:87], v[160:161], s[18:19], v[86:87] op_sel_hi:[1,0,1]
	v_pk_fma_f32 v[16:17], v[150:151], s[18:19], v[16:17] op_sel_hi:[1,0,1]
	v_pk_fma_f32 v[114:115], v[148:149], s[18:19], v[114:115] op_sel_hi:[1,0,1]
	v_pk_fma_f32 v[124:125], v[144:145], s[18:19], v[124:125] op_sel_hi:[1,0,1]
	v_pk_fma_f32 v[20:21], v[140:141], s[18:19], v[20:21] op_sel_hi:[1,0,1]
	v_pk_fma_f32 v[120:121], v[136:137], s[18:19], v[120:121] op_sel_hi:[1,0,1]
	v_pk_fma_f32 v[28:29], v[132:133], s[18:19], v[28:29] op_sel_hi:[1,0,1]
	v_addc_co_u32_e32 v139, vcc, 0, v147, vcc
	s_mov_b64 s[0:1], 0xa0000
	global_load_dwordx4 v[130:133], v[130:131], off
	s_nop 0
	global_load_dwordx4 v[134:137], v[134:135], off offset:256
	s_nop 0
	global_load_dwordx4 v[138:141], v[138:139], off
	s_nop 0
	global_load_dwordx4 v[154:157], v[142:143], off offset:256
	v_lshl_add_u64 v[142:143], v[146:147], 0, s[0:1]
	s_mov_b32 s0, 0xa0000
	v_add_co_u32_e32 v144, vcc, s0, v146
	s_mov_b64 s[0:1], 0xb0000
	s_nop 0
	v_addc_co_u32_e32 v145, vcc, 0, v147, vcc
	global_load_dwordx4 v[158:161], v[144:145], off
	global_load_dwordx4 v[170:173], v[142:143], off offset:256
	v_lshl_add_u64 v[142:143], v[146:147], 0, s[0:1]
	s_mov_b32 s0, 0xb0000
	v_add_co_u32_e32 v144, vcc, s0, v146
	s_movk_i32 s0, 0x2000
	s_nop 0
	v_addc_co_u32_e32 v145, vcc, 0, v147, vcc
	global_load_dwordx4 v[150:153], v[144:145], off
	global_load_dwordx4 v[146:149], v[142:143], off offset:256
	s_waitcnt vmcnt(0)
	s_nop 0
	v_lshlrev_b32_e32 v142, 16, v130
	v_and_b32_e32 v143, 0xffff0000, v130
	v_lshlrev_b32_e32 v130, 16, v131
	v_and_b32_e32 v131, 0xffff0000, v131
	v_pk_fma_f32 v[112:113], v[130:131], s[18:19], v[112:113] op_sel_hi:[1,0,1]
	v_lshlrev_b32_e32 v130, 16, v132
	v_and_b32_e32 v131, 0xffff0000, v132
	v_lshlrev_b32_e32 v132, 16, v133
	v_and_b32_e32 v133, 0xffff0000, v133
	v_pk_fma_f32 v[130:131], v[130:131], s[18:19], v[106:107] op_sel_hi:[1,0,1]
	v_lshlrev_b32_e32 v106, 16, v134
	v_and_b32_e32 v107, 0xffff0000, v134
	v_pk_fma_f32 v[132:133], v[132:133], s[18:19], v[108:109] op_sel_hi:[1,0,1]
	v_lshlrev_b32_e32 v108, 16, v135
	v_and_b32_e32 v109, 0xffff0000, v135
	v_pk_fma_f32 v[38:39], v[106:107], s[18:19], v[38:39] op_sel_hi:[1,0,1]
	v_lshlrev_b32_e32 v106, 16, v136
	v_and_b32_e32 v107, 0xffff0000, v136
	v_pk_fma_f32 v[40:41], v[108:109], s[18:19], v[40:41] op_sel_hi:[1,0,1]
	v_lshlrev_b32_e32 v108, 16, v137
	v_and_b32_e32 v109, 0xffff0000, v137
	v_pk_fma_f32 v[34:35], v[106:107], s[18:19], v[34:35] op_sel_hi:[1,0,1]
	v_lshlrev_b32_e32 v106, 16, v138
	v_and_b32_e32 v107, 0xffff0000, v138
	v_pk_fma_f32 v[110:111], v[142:143], s[18:19], v[110:111] op_sel_hi:[1,0,1]
	v_pk_fma_f32 v[36:37], v[108:109], s[18:19], v[36:37] op_sel_hi:[1,0,1]
	v_lshlrev_b32_e32 v108, 16, v139
	v_and_b32_e32 v109, 0xffff0000, v139
	v_pk_fma_f32 v[142:143], v[106:107], s[18:19], v[90:91] op_sel_hi:[1,0,1]
	v_lshlrev_b32_e32 v90, 16, v140
	v_and_b32_e32 v91, 0xffff0000, v140
	v_pk_fma_f32 v[144:145], v[108:109], s[18:19], v[92:93] op_sel_hi:[1,0,1]
	v_lshlrev_b32_e32 v92, 16, v141
	v_and_b32_e32 v93, 0xffff0000, v141
	v_pk_fma_f32 v[106:107], v[90:91], s[18:19], v[82:83] op_sel_hi:[1,0,1]
	v_lshlrev_b32_e32 v82, 16, v154
	v_and_b32_e32 v83, 0xffff0000, v154
	v_pk_fma_f32 v[108:109], v[92:93], s[18:19], v[84:85] op_sel_hi:[1,0,1]
	v_lshlrev_b32_e32 v84, 16, v155
	v_and_b32_e32 v85, 0xffff0000, v155
	v_pk_fma_f32 v[46:47], v[82:83], s[18:19], v[46:47] op_sel_hi:[1,0,1]
	v_lshlrev_b32_e32 v82, 16, v156
	v_and_b32_e32 v83, 0xffff0000, v156
	v_pk_fma_f32 v[48:49], v[84:85], s[18:19], v[48:49] op_sel_hi:[1,0,1]
	v_lshlrev_b32_e32 v84, 16, v157
	v_and_b32_e32 v85, 0xffff0000, v157
	v_pk_fma_f32 v[42:43], v[82:83], s[18:19], v[42:43] op_sel_hi:[1,0,1]
	v_lshlrev_b32_e32 v82, 16, v158
	v_and_b32_e32 v83, 0xffff0000, v158
	v_pk_fma_f32 v[44:45], v[84:85], s[18:19], v[44:45] op_sel_hi:[1,0,1]
	v_lshlrev_b32_e32 v84, 16, v159
	v_and_b32_e32 v85, 0xffff0000, v159
	v_pk_fma_f32 v[138:139], v[82:83], s[18:19], v[78:79] op_sel_hi:[1,0,1]
	v_lshlrev_b32_e32 v78, 16, v160
	v_and_b32_e32 v79, 0xffff0000, v160
	v_pk_fma_f32 v[140:141], v[84:85], s[18:19], v[80:81] op_sel_hi:[1,0,1]
	v_lshlrev_b32_e32 v80, 16, v161
	v_and_b32_e32 v81, 0xffff0000, v161
	v_pk_fma_f32 v[90:91], v[78:79], s[18:19], v[74:75] op_sel_hi:[1,0,1]
	v_lshlrev_b32_e32 v74, 16, v170
	v_and_b32_e32 v75, 0xffff0000, v170
	v_pk_fma_f32 v[92:93], v[80:81], s[18:19], v[76:77] op_sel_hi:[1,0,1]
	v_lshlrev_b32_e32 v76, 16, v171
	v_and_b32_e32 v77, 0xffff0000, v171
	v_pk_fma_f32 v[54:55], v[74:75], s[18:19], v[54:55] op_sel_hi:[1,0,1]
	v_lshlrev_b32_e32 v74, 16, v172
	v_and_b32_e32 v75, 0xffff0000, v172
	v_pk_fma_f32 v[56:57], v[76:77], s[18:19], v[56:57] op_sel_hi:[1,0,1]
	v_lshlrev_b32_e32 v76, 16, v173
	v_and_b32_e32 v77, 0xffff0000, v173
	v_pk_fma_f32 v[50:51], v[74:75], s[18:19], v[50:51] op_sel_hi:[1,0,1]
	v_lshlrev_b32_e32 v74, 16, v150
	v_and_b32_e32 v75, 0xffff0000, v150
	v_pk_fma_f32 v[52:53], v[76:77], s[18:19], v[52:53] op_sel_hi:[1,0,1]
	v_lshlrev_b32_e32 v76, 16, v151
	v_and_b32_e32 v77, 0xffff0000, v151
	v_pk_fma_f32 v[134:135], v[74:75], s[18:19], v[70:71] op_sel_hi:[1,0,1]
	v_lshlrev_b32_e32 v70, 16, v152
	v_and_b32_e32 v71, 0xffff0000, v152
	v_pk_fma_f32 v[136:137], v[76:77], s[18:19], v[72:73] op_sel_hi:[1,0,1]
	v_lshlrev_b32_e32 v72, 16, v153
	v_and_b32_e32 v73, 0xffff0000, v153
	v_pk_fma_f32 v[82:83], v[70:71], s[18:19], v[66:67] op_sel_hi:[1,0,1]
	v_lshlrev_b32_e32 v66, 16, v146
	v_and_b32_e32 v67, 0xffff0000, v146
	v_pk_fma_f32 v[84:85], v[72:73], s[18:19], v[68:69] op_sel_hi:[1,0,1]
	v_lshlrev_b32_e32 v68, 16, v147
	v_and_b32_e32 v69, 0xffff0000, v147
	v_pk_fma_f32 v[62:63], v[66:67], s[18:19], v[62:63] op_sel_hi:[1,0,1]
	v_lshlrev_b32_e32 v66, 16, v148
	v_and_b32_e32 v67, 0xffff0000, v148
	v_pk_fma_f32 v[64:65], v[68:69], s[18:19], v[64:65] op_sel_hi:[1,0,1]
	v_lshlrev_b32_e32 v68, 16, v149
	v_and_b32_e32 v69, 0xffff0000, v149
	v_pk_fma_f32 v[58:59], v[66:67], s[18:19], v[58:59] op_sel_hi:[1,0,1]
	v_lshlrev_b64 v[66:67], 2, v[164:165]
	v_pk_fma_f32 v[60:61], v[68:69], s[18:19], v[60:61] op_sel_hi:[1,0,1]
	v_lshl_add_u64 v[68:69], s[4:5], 0, v[66:67]
	v_lshl_add_u64 v[70:71], v[68:69], 0, s[40:41]
	v_add_co_u32_e32 v68, vcc, s0, v68
	v_lshl_add_u64 v[66:67], s[6:7], 0, v[66:67]
	s_nop 0
	v_addc_co_u32_e32 v69, vcc, 0, v69, vcc
	v_lshl_add_u64 v[78:79], v[66:67], 0, s[40:41]
	v_add_co_u32_e32 v66, vcc, s0, v66
	s_nop 1
	v_addc_co_u32_e32 v67, vcc, 0, v67, vcc
	global_load_dwordx4 v[154:157], v[68:69], off
	global_load_dwordx4 v[146:149], v[70:71], off offset:16
	global_load_dwordx4 v[158:161], v[66:67], off
	global_load_dwordx4 v[150:153], v[78:79], off offset:16
	s_nop 0
	global_load_dwordx4 v[66:69], v[70:71], off offset:528
	global_load_dwordx4 v[74:77], v[70:71], off offset:512
	s_nop 0
	global_load_dwordx4 v[70:73], v[78:79], off offset:528
	s_nop 0
	global_load_dwordx4 v[78:81], v[78:79], off offset:512
	v_cmp_lt_i32_e32 vcc, v167, v169
	v_xor_b32_e32 v170, 32, v219
	v_mov_b32_e32 v171, v88
	v_cndmask_b32_e32 v167, v219, v167, vcc
	v_cmp_lt_i32_e32 vcc, v170, v169
	v_mov_b32_e32 v172, v86
	v_mov_b32_e32 v173, v89
	v_cndmask_b32_e32 v169, v219, v170, vcc
	v_mov_b32_e32 v170, v87
	v_pk_add_f32 v[170:171], v[170:171], v[172:173]
	v_mov_b32_e32 v172, v95
	v_mov_b32_e32 v173, v96
	v_mov_b32_e32 v174, v94
	v_mov_b32_e32 v175, v97
	v_pk_add_f32 v[172:173], v[172:173], v[174:175]
	v_add_f32_e32 v170, v170, v171
	v_pk_add_f32 v[172:173], v[172:173], v[172:173] op_sel_hi:[0,1]
	v_add_f32_e32 v171, 0, v170
	v_add_f32_e32 v175, v2, v3
	v_add_f32_e32 v177, v4, v5
	v_mov_b32_e32 v174, v6
	v_mov_b32_e32 v176, v7
	v_mov_b32_e32 v172, v8
	v_mov_b32_e32 v170, v9
	v_pk_add_f32 v[174:175], v[174:175], v[176:177]
	v_pk_add_f32 v[170:171], v[172:173], v[170:171]
	v_lshlrev_b32_e32 v167, 2, v167
	v_pk_add_f32 v[170:171], v[174:175], v[170:171]
	v_lshlrev_b32_e32 v169, 2, v169
	v_add_f32_e32 v170, v170, v171
	v_mov_b32_e32 v171, v170
	s_nop 1
	v_permlane16_swap_b32 v171, v170
	s_lshl_b32 s0, s10, 3
	s_add_i32 s0, s0, 0
	v_cmp_gt_u32_e32 vcc, 16, v168
	v_add_f32_e32 v170, v170, v171
	v_mov_b32_e32 v171, v170
	s_nop 1
	v_permlane32_swap_b32 v171, v170
	v_add_f32_e32 v171, v170, v171
	v_fmamk_f32 v172, v171, 0xbc800000, v89
	v_fmamk_f32 v174, v171, 0xbc800000, v87
	v_fmamk_f32 v170, v171, 0xbc800000, v88
	v_fmamk_f32 v173, v171, 0xbc800000, v86
	v_mul_f32_e32 v174, v174, v174
	v_mul_f32_e32 v172, v172, v172
	v_fmac_f32_e32 v174, v173, v173
	v_fmac_f32_e32 v172, v170, v170
	v_fmamk_f32 v173, v171, 0xbc800000, v97
	v_fmamk_f32 v175, v171, 0xbc800000, v95
	v_add_f32_e32 v170, v174, v172
	v_fmamk_f32 v172, v171, 0xbc800000, v96
	v_fmamk_f32 v174, v171, 0xbc800000, v94
	v_mul_f32_e32 v175, v175, v175
	v_mul_f32_e32 v173, v173, v173
	v_fmac_f32_e32 v175, v174, v174
	v_fmac_f32_e32 v173, v172, v172
	v_add_f32_e32 v172, v175, v173
	v_fmamk_f32 v173, v171, 0xbc800000, v5
	v_fmamk_f32 v175, v171, 0xbc800000, v3
	v_add_f32_e32 v170, v170, v172
	v_fmamk_f32 v172, v171, 0xbc800000, v4
	v_fmamk_f32 v174, v171, 0xbc800000, v2
	v_mul_f32_e32 v175, v175, v175
	v_mul_f32_e32 v173, v173, v173
	v_fmac_f32_e32 v175, v174, v174
	v_fmac_f32_e32 v173, v172, v172
	v_add_f32_e32 v172, v175, v173
	v_fmamk_f32 v173, v171, 0xbc800000, v9
	v_fmamk_f32 v175, v171, 0xbc800000, v7
	v_add_f32_e32 v170, v172, v170
	v_fmamk_f32 v172, v171, 0xbc800000, v8
	v_fmamk_f32 v174, v171, 0xbc800000, v6
	v_mul_f32_e32 v175, v175, v175
	v_mul_f32_e32 v173, v173, v173
	v_fmac_f32_e32 v175, v174, v174
	v_fmac_f32_e32 v173, v172, v172
	v_add_f32_e32 v172, v175, v173
	v_add_f32_e32 v170, v172, v170
	v_mov_b32_e32 v172, v170
	s_nop 1
	v_permlane16_swap_b32 v172, v170
	v_add_f32_e32 v172, v170, v172
	v_mov_b32_e32 v173, v172
	s_nop 1
	v_permlane32_swap_b32 v173, v172
	v_lshl_add_u32 v170, v1, 5, s0
	s_and_saveexec_b64 s[0:1], vcc
	v_readlane_b32 s38, v255, 28
	v_readlane_b32 s44, v255, 30
	v_readlane_b32 s39, v255, 29
	v_readlane_b32 s45, v255, 31
	v_readlane_b32 s42, v255, 32
	s_cbranch_execz .LBB0_821
	v_mul_f32_e32 v174, 0x3c800000, v171
	v_add_f32_e32 v175, v172, v173
	ds_write_b64 v170, v[174:175]
.LBB0_821:
	s_or_b64 exec, exec, s[0:1]
	v_mov_b32_e32 v172, v99
	v_mov_b32_e32 v173, v100
	v_mov_b32_e32 v174, v98
	v_mov_b32_e32 v175, v101
	v_pk_add_f32 v[172:173], v[172:173], v[174:175]
	v_mov_b32_e32 v174, v103
	v_mov_b32_e32 v175, v104
	v_mov_b32_e32 v176, v102
	v_mov_b32_e32 v177, v105
	v_pk_add_f32 v[174:175], v[174:175], v[176:177]
	v_add_f32_e32 v171, v172, v173
	v_pk_add_f32 v[174:175], v[174:175], v[174:175] op_sel_hi:[0,1]
	v_add_f32_e32 v173, 0, v171
	v_add_f32_e32 v177, v10, v11
	v_add_f32_e32 v179, v12, v13
	v_mov_b32_e32 v176, v14
	v_mov_b32_e32 v178, v15
	v_mov_b32_e32 v174, v16
	v_mov_b32_e32 v172, v17
	v_pk_add_f32 v[176:177], v[176:177], v[178:179]
	v_pk_add_f32 v[172:173], v[174:175], v[172:173]
	s_nop 0
	v_pk_add_f32 v[172:173], v[176:177], v[172:173]
	s_nop 0
	v_add_f32_e32 v171, v172, v173
	v_mov_b32_e32 v172, v171
	s_nop 1
	v_permlane16_swap_b32 v172, v171
	v_add_f32_e32 v171, v171, v172
	v_mov_b32_e32 v172, v171
	s_nop 1
	v_permlane32_swap_b32 v172, v171
	v_add_f32_e32 v171, v171, v172
	v_fmamk_f32 v173, v171, 0xbc800000, v101
	v_fmamk_f32 v175, v171, 0xbc800000, v99
	v_fmamk_f32 v172, v171, 0xbc800000, v100
	v_fmamk_f32 v174, v171, 0xbc800000, v98
	v_mul_f32_e32 v175, v175, v175
	v_mul_f32_e32 v173, v173, v173
	v_fmac_f32_e32 v175, v174, v174
	v_fmac_f32_e32 v173, v172, v172
	v_fmamk_f32 v174, v171, 0xbc800000, v105
	v_fmamk_f32 v176, v171, 0xbc800000, v103
	v_add_f32_e32 v172, v175, v173
	v_fmamk_f32 v173, v171, 0xbc800000, v104
	v_fmamk_f32 v175, v171, 0xbc800000, v102
	v_mul_f32_e32 v176, v176, v176
	v_mul_f32_e32 v174, v174, v174
	v_fmac_f32_e32 v176, v175, v175
	v_fmac_f32_e32 v174, v173, v173
	v_add_f32_e32 v173, v176, v174
	v_fmamk_f32 v174, v171, 0xbc800000, v13
	v_fmamk_f32 v176, v171, 0xbc800000, v11
	v_add_f32_e32 v172, v172, v173
	v_fmamk_f32 v173, v171, 0xbc800000, v12
	v_fmamk_f32 v175, v171, 0xbc800000, v10
	v_mul_f32_e32 v176, v176, v176
	v_mul_f32_e32 v174, v174, v174
	v_fmac_f32_e32 v176, v175, v175
	v_fmac_f32_e32 v174, v173, v173
	v_add_f32_e32 v173, v176, v174
	v_fmamk_f32 v174, v171, 0xbc800000, v17
	v_fmamk_f32 v176, v171, 0xbc800000, v15
	v_add_f32_e32 v172, v173, v172
	v_fmamk_f32 v173, v171, 0xbc800000, v16
	v_fmamk_f32 v175, v171, 0xbc800000, v14
	v_mul_f32_e32 v176, v176, v176
	v_mul_f32_e32 v174, v174, v174
	v_fmac_f32_e32 v176, v175, v175
	v_fmac_f32_e32 v174, v173, v173
	v_add_f32_e32 v173, v176, v174
	v_add_f32_e32 v172, v173, v172
	v_mov_b32_e32 v173, v172
	s_nop 1
	v_permlane16_swap_b32 v173, v172
	v_add_f32_e32 v172, v172, v173
	v_mov_b32_e32 v173, v172
	s_nop 1
	v_permlane32_swap_b32 v173, v172
	s_and_saveexec_b64 s[0:1], vcc
	s_cbranch_execz .LBB0_823
	v_mul_f32_e32 v174, 0x3c800000, v171
	v_add_f32_e32 v175, v172, v173
	ds_write_b64 v170, v[174:175] offset:512
.LBB0_823:
	s_or_b64 exec, exec, s[0:1]
	v_mov_b32_e32 v172, v115
	v_mov_b32_e32 v173, v116
	v_mov_b32_e32 v174, v114
	v_mov_b32_e32 v175, v117
	v_pk_add_f32 v[172:173], v[172:173], v[174:175]
	v_mov_b32_e32 v174, v123
	v_mov_b32_e32 v175, v124
	v_mov_b32_e32 v176, v122
	v_mov_b32_e32 v177, v125
	v_pk_add_f32 v[174:175], v[174:175], v[176:177]
	v_add_f32_e32 v171, v172, v173
	v_pk_add_f32 v[174:175], v[174:175], v[174:175] op_sel_hi:[0,1]
	v_add_f32_e32 v173, 0, v171
	v_add_f32_e32 v177, v22, v23
	v_add_f32_e32 v179, v24, v25
	v_mov_b32_e32 v176, v18
	v_mov_b32_e32 v178, v19
	v_mov_b32_e32 v174, v20
	v_mov_b32_e32 v172, v21
	v_pk_add_f32 v[176:177], v[176:177], v[178:179]
	v_pk_add_f32 v[172:173], v[174:175], v[172:173]
	s_nop 0
	v_pk_add_f32 v[172:173], v[176:177], v[172:173]
	s_nop 0
	v_add_f32_e32 v171, v172, v173
	v_mov_b32_e32 v172, v171
	s_nop 1
	v_permlane16_swap_b32 v172, v171
	v_add_f32_e32 v171, v171, v172
	v_mov_b32_e32 v172, v171
	s_nop 1
	v_permlane32_swap_b32 v172, v171
	v_add_f32_e32 v171, v171, v172
	v_fmamk_f32 v173, v171, 0xbc800000, v117
	v_fmamk_f32 v175, v171, 0xbc800000, v115
	v_fmamk_f32 v172, v171, 0xbc800000, v116
	v_fmamk_f32 v174, v171, 0xbc800000, v114
	v_mul_f32_e32 v175, v175, v175
	v_mul_f32_e32 v173, v173, v173
	v_fmac_f32_e32 v175, v174, v174
	v_fmac_f32_e32 v173, v172, v172
	v_fmamk_f32 v174, v171, 0xbc800000, v125
	v_fmamk_f32 v176, v171, 0xbc800000, v123
	v_add_f32_e32 v172, v175, v173
	v_fmamk_f32 v173, v171, 0xbc800000, v124
	v_fmamk_f32 v175, v171, 0xbc800000, v122
	v_mul_f32_e32 v176, v176, v176
	v_mul_f32_e32 v174, v174, v174
	v_fmac_f32_e32 v176, v175, v175
	v_fmac_f32_e32 v174, v173, v173
	v_add_f32_e32 v173, v176, v174
	v_fmamk_f32 v174, v171, 0xbc800000, v25
	v_fmamk_f32 v176, v171, 0xbc800000, v23
	v_add_f32_e32 v172, v172, v173
	v_fmamk_f32 v173, v171, 0xbc800000, v24
	v_fmamk_f32 v175, v171, 0xbc800000, v22
	v_mul_f32_e32 v176, v176, v176
	v_mul_f32_e32 v174, v174, v174
	v_fmac_f32_e32 v176, v175, v175
	v_fmac_f32_e32 v174, v173, v173
	v_add_f32_e32 v173, v176, v174
	v_fmamk_f32 v174, v171, 0xbc800000, v21
	v_fmamk_f32 v176, v171, 0xbc800000, v19
	v_add_f32_e32 v172, v173, v172
	v_fmamk_f32 v173, v171, 0xbc800000, v20
	v_fmamk_f32 v175, v171, 0xbc800000, v18
	v_mul_f32_e32 v176, v176, v176
	v_mul_f32_e32 v174, v174, v174
	v_fmac_f32_e32 v176, v175, v175
	v_fmac_f32_e32 v174, v173, v173
	v_add_f32_e32 v173, v176, v174
	v_add_f32_e32 v172, v173, v172
	v_mov_b32_e32 v173, v172
	s_nop 1
	v_permlane16_swap_b32 v173, v172
	v_add_f32_e32 v172, v172, v173
	v_mov_b32_e32 v173, v172
	s_nop 1
	v_permlane32_swap_b32 v173, v172
	s_and_saveexec_b64 s[0:1], vcc
	s_cbranch_execz .LBB0_825
	v_mul_f32_e32 v174, 0x3c800000, v171
	v_add_f32_e32 v175, v172, v173
	ds_write_b64 v170, v[174:175] offset:1024
.LBB0_825:
	s_or_b64 exec, exec, s[0:1]
	v_mov_b32_e32 v172, v127
	v_mov_b32_e32 v173, v128
	v_mov_b32_e32 v174, v126
	v_mov_b32_e32 v175, v129
	v_pk_add_f32 v[172:173], v[172:173], v[174:175]
	v_mov_b32_e32 v174, v119
	v_mov_b32_e32 v175, v120
	v_mov_b32_e32 v176, v118
	v_mov_b32_e32 v177, v121
	v_pk_add_f32 v[174:175], v[174:175], v[176:177]
	v_add_f32_e32 v171, v172, v173
	v_pk_add_f32 v[174:175], v[174:175], v[174:175] op_sel_hi:[0,1]
	v_add_f32_e32 v173, 0, v171
	v_add_f32_e32 v177, v30, v31
	v_add_f32_e32 v179, v32, v33
	v_mov_b32_e32 v176, v26
	v_mov_b32_e32 v178, v27
	v_mov_b32_e32 v174, v28
	v_mov_b32_e32 v172, v29
	v_pk_add_f32 v[176:177], v[176:177], v[178:179]
	v_pk_add_f32 v[172:173], v[174:175], v[172:173]
	s_nop 0
	v_pk_add_f32 v[172:173], v[176:177], v[172:173]
	s_nop 0
	v_add_f32_e32 v171, v172, v173
	v_mov_b32_e32 v172, v171
	s_nop 1
	v_permlane16_swap_b32 v172, v171
	v_add_f32_e32 v171, v171, v172
	v_mov_b32_e32 v172, v171
	s_nop 1
	v_permlane32_swap_b32 v172, v171
	v_add_f32_e32 v171, v171, v172
	v_fmamk_f32 v173, v171, 0xbc800000, v129
	v_fmamk_f32 v175, v171, 0xbc800000, v127
	v_fmamk_f32 v172, v171, 0xbc800000, v128
	v_fmamk_f32 v174, v171, 0xbc800000, v126
	v_mul_f32_e32 v175, v175, v175
	v_mul_f32_e32 v173, v173, v173
	v_fmac_f32_e32 v175, v174, v174
	v_fmac_f32_e32 v173, v172, v172
	v_fmamk_f32 v174, v171, 0xbc800000, v121
	v_fmamk_f32 v176, v171, 0xbc800000, v119
	v_add_f32_e32 v172, v175, v173
	v_fmamk_f32 v173, v171, 0xbc800000, v120
	v_fmamk_f32 v175, v171, 0xbc800000, v118
	v_mul_f32_e32 v176, v176, v176
	v_mul_f32_e32 v174, v174, v174
	v_fmac_f32_e32 v176, v175, v175
	v_fmac_f32_e32 v174, v173, v173
	v_add_f32_e32 v173, v176, v174
	v_fmamk_f32 v174, v171, 0xbc800000, v33
	v_fmamk_f32 v176, v171, 0xbc800000, v31
	v_add_f32_e32 v172, v172, v173
	v_fmamk_f32 v173, v171, 0xbc800000, v32
	v_fmamk_f32 v175, v171, 0xbc800000, v30
	v_mul_f32_e32 v176, v176, v176
	v_mul_f32_e32 v174, v174, v174
	v_fmac_f32_e32 v176, v175, v175
	v_fmac_f32_e32 v174, v173, v173
	v_add_f32_e32 v173, v176, v174
	v_fmamk_f32 v174, v171, 0xbc800000, v29
	v_fmamk_f32 v176, v171, 0xbc800000, v27
	v_add_f32_e32 v172, v173, v172
	v_fmamk_f32 v173, v171, 0xbc800000, v28
	v_fmamk_f32 v175, v171, 0xbc800000, v26
	v_mul_f32_e32 v176, v176, v176
	v_mul_f32_e32 v174, v174, v174
	v_fmac_f32_e32 v176, v175, v175
	v_fmac_f32_e32 v174, v173, v173
	v_add_f32_e32 v173, v176, v174
	v_add_f32_e32 v172, v173, v172
	v_mov_b32_e32 v173, v172
	s_nop 1
	v_permlane16_swap_b32 v173, v172
	v_add_f32_e32 v172, v172, v173
	v_mov_b32_e32 v173, v172
	s_nop 1
	v_permlane32_swap_b32 v173, v172
	s_and_saveexec_b64 s[0:1], vcc
	s_cbranch_execz .LBB0_827
	v_mul_f32_e32 v174, 0x3c800000, v171
	v_add_f32_e32 v175, v172, v173
	ds_write_b64 v170, v[174:175] offset:1536
.LBB0_827:
	s_or_b64 exec, exec, s[0:1]
	v_mov_b32_e32 v172, v111
	v_mov_b32_e32 v173, v112
	v_mov_b32_e32 v174, v110
	v_mov_b32_e32 v175, v113
	v_pk_add_f32 v[172:173], v[172:173], v[174:175]
	v_mov_b32_e32 v174, v131
	v_mov_b32_e32 v175, v132
	v_mov_b32_e32 v176, v130
	v_mov_b32_e32 v177, v133
	v_pk_add_f32 v[174:175], v[174:175], v[176:177]
	v_add_f32_e32 v171, v172, v173
	v_pk_add_f32 v[174:175], v[174:175], v[174:175] op_sel_hi:[0,1]
	v_add_f32_e32 v173, 0, v171
	v_add_f32_e32 v177, v38, v39
	v_add_f32_e32 v179, v40, v41
	v_mov_b32_e32 v176, v34
	v_mov_b32_e32 v178, v35
	v_mov_b32_e32 v174, v36
	v_mov_b32_e32 v172, v37
	v_pk_add_f32 v[176:177], v[176:177], v[178:179]
	v_pk_add_f32 v[172:173], v[174:175], v[172:173]
	s_nop 0
	v_pk_add_f32 v[172:173], v[176:177], v[172:173]
	s_nop 0
	v_add_f32_e32 v171, v172, v173
	v_mov_b32_e32 v172, v171
	s_nop 1
	v_permlane16_swap_b32 v172, v171
	v_add_f32_e32 v171, v171, v172
	v_mov_b32_e32 v172, v171
	s_nop 1
	v_permlane32_swap_b32 v172, v171
	v_add_f32_e32 v171, v171, v172
	v_fmamk_f32 v173, v171, 0xbc800000, v113
	v_fmamk_f32 v175, v171, 0xbc800000, v111
	v_fmamk_f32 v172, v171, 0xbc800000, v112
	v_fmamk_f32 v174, v171, 0xbc800000, v110
	v_mul_f32_e32 v175, v175, v175
	v_mul_f32_e32 v173, v173, v173
	v_fmac_f32_e32 v175, v174, v174
	v_fmac_f32_e32 v173, v172, v172
	v_fmamk_f32 v174, v171, 0xbc800000, v133
	v_fmamk_f32 v176, v171, 0xbc800000, v131
	v_add_f32_e32 v172, v175, v173
	v_fmamk_f32 v173, v171, 0xbc800000, v132
	v_fmamk_f32 v175, v171, 0xbc800000, v130
	v_mul_f32_e32 v176, v176, v176
	v_mul_f32_e32 v174, v174, v174
	v_fmac_f32_e32 v176, v175, v175
	v_fmac_f32_e32 v174, v173, v173
	v_add_f32_e32 v173, v176, v174
	v_fmamk_f32 v174, v171, 0xbc800000, v41
	v_fmamk_f32 v176, v171, 0xbc800000, v39
	v_add_f32_e32 v172, v172, v173
	v_fmamk_f32 v173, v171, 0xbc800000, v40
	v_fmamk_f32 v175, v171, 0xbc800000, v38
	v_mul_f32_e32 v176, v176, v176
	v_mul_f32_e32 v174, v174, v174
	v_fmac_f32_e32 v176, v175, v175
	v_fmac_f32_e32 v174, v173, v173
	v_add_f32_e32 v173, v176, v174
	v_fmamk_f32 v174, v171, 0xbc800000, v37
	v_fmamk_f32 v176, v171, 0xbc800000, v35
	v_add_f32_e32 v172, v173, v172
	v_fmamk_f32 v173, v171, 0xbc800000, v36
	v_fmamk_f32 v175, v171, 0xbc800000, v34
	v_mul_f32_e32 v176, v176, v176
	v_mul_f32_e32 v174, v174, v174
	v_fmac_f32_e32 v176, v175, v175
	v_fmac_f32_e32 v174, v173, v173
	v_add_f32_e32 v173, v176, v174
	v_add_f32_e32 v172, v173, v172
	v_mov_b32_e32 v173, v172
	s_nop 1
	v_permlane16_swap_b32 v173, v172
	v_add_f32_e32 v172, v172, v173
	v_mov_b32_e32 v173, v172
	s_nop 1
	v_permlane32_swap_b32 v173, v172
	s_and_saveexec_b64 s[0:1], vcc
	s_cbranch_execz .LBB0_829
	v_mul_f32_e32 v174, 0x3c800000, v171
	v_add_f32_e32 v175, v172, v173
	ds_write_b64 v170, v[174:175] offset:4096
.LBB0_829:
	s_or_b64 exec, exec, s[0:1]
	v_mov_b32_e32 v172, v143
	v_mov_b32_e32 v173, v144
	v_mov_b32_e32 v174, v142
	v_mov_b32_e32 v175, v145
	v_pk_add_f32 v[172:173], v[172:173], v[174:175]
	v_mov_b32_e32 v174, v107
	v_mov_b32_e32 v175, v108
	v_mov_b32_e32 v176, v106
	v_mov_b32_e32 v177, v109
	v_pk_add_f32 v[174:175], v[174:175], v[176:177]
	v_add_f32_e32 v171, v172, v173
	v_pk_add_f32 v[174:175], v[174:175], v[174:175] op_sel_hi:[0,1]
	v_add_f32_e32 v173, 0, v171
	v_add_f32_e32 v177, v46, v47
	v_add_f32_e32 v179, v48, v49
	v_mov_b32_e32 v176, v42
	v_mov_b32_e32 v178, v43
	v_mov_b32_e32 v174, v44
	v_mov_b32_e32 v172, v45
	v_pk_add_f32 v[176:177], v[176:177], v[178:179]
	v_pk_add_f32 v[172:173], v[174:175], v[172:173]
	s_nop 0
	v_pk_add_f32 v[172:173], v[176:177], v[172:173]
	s_nop 0
	v_add_f32_e32 v171, v172, v173
	v_mov_b32_e32 v172, v171
	s_nop 1
	v_permlane16_swap_b32 v172, v171
	v_add_f32_e32 v171, v171, v172
	v_mov_b32_e32 v172, v171
	s_nop 1
	v_permlane32_swap_b32 v172, v171
	v_add_f32_e32 v171, v171, v172
	v_fmamk_f32 v173, v171, 0xbc800000, v145
	v_fmamk_f32 v175, v171, 0xbc800000, v143
	v_fmamk_f32 v172, v171, 0xbc800000, v144
	v_fmamk_f32 v174, v171, 0xbc800000, v142
	v_mul_f32_e32 v175, v175, v175
	v_mul_f32_e32 v173, v173, v173
	v_fmac_f32_e32 v175, v174, v174
	v_fmac_f32_e32 v173, v172, v172
	v_fmamk_f32 v174, v171, 0xbc800000, v109
	v_fmamk_f32 v176, v171, 0xbc800000, v107
	v_add_f32_e32 v172, v175, v173
	v_fmamk_f32 v173, v171, 0xbc800000, v108
	v_fmamk_f32 v175, v171, 0xbc800000, v106
	v_mul_f32_e32 v176, v176, v176
	v_mul_f32_e32 v174, v174, v174
	v_fmac_f32_e32 v176, v175, v175
	v_fmac_f32_e32 v174, v173, v173
	v_add_f32_e32 v173, v176, v174
	v_fmamk_f32 v174, v171, 0xbc800000, v49
	v_fmamk_f32 v176, v171, 0xbc800000, v47
	v_add_f32_e32 v172, v172, v173
	v_fmamk_f32 v173, v171, 0xbc800000, v48
	v_fmamk_f32 v175, v171, 0xbc800000, v46
	v_mul_f32_e32 v176, v176, v176
	v_mul_f32_e32 v174, v174, v174
	v_fmac_f32_e32 v176, v175, v175
	v_fmac_f32_e32 v174, v173, v173
	v_add_f32_e32 v173, v176, v174
	v_fmamk_f32 v174, v171, 0xbc800000, v45
	v_fmamk_f32 v176, v171, 0xbc800000, v43
	v_add_f32_e32 v172, v173, v172
	v_fmamk_f32 v173, v171, 0xbc800000, v44
	v_fmamk_f32 v175, v171, 0xbc800000, v42
	v_mul_f32_e32 v176, v176, v176
	v_mul_f32_e32 v174, v174, v174
	v_fmac_f32_e32 v176, v175, v175
	v_fmac_f32_e32 v174, v173, v173
	v_add_f32_e32 v173, v176, v174
	v_add_f32_e32 v172, v173, v172
	v_mov_b32_e32 v173, v172
	s_nop 1
	v_permlane16_swap_b32 v173, v172
	v_add_f32_e32 v172, v172, v173
	v_mov_b32_e32 v173, v172
	s_nop 1
	v_permlane32_swap_b32 v173, v172
	s_and_saveexec_b64 s[0:1], vcc
	s_cbranch_execz .LBB0_831
	v_mul_f32_e32 v174, 0x3c800000, v171
	v_add_f32_e32 v175, v172, v173
	ds_write_b64 v170, v[174:175] offset:4608
.LBB0_831:
	s_or_b64 exec, exec, s[0:1]
	v_mov_b32_e32 v172, v139
	v_mov_b32_e32 v173, v140
	v_mov_b32_e32 v174, v138
	v_mov_b32_e32 v175, v141
	v_pk_add_f32 v[172:173], v[172:173], v[174:175]
	v_mov_b32_e32 v174, v91
	v_mov_b32_e32 v175, v92
	v_mov_b32_e32 v176, v90
	v_mov_b32_e32 v177, v93
	v_pk_add_f32 v[174:175], v[174:175], v[176:177]
	v_add_f32_e32 v171, v172, v173
	v_pk_add_f32 v[174:175], v[174:175], v[174:175] op_sel_hi:[0,1]
	v_add_f32_e32 v173, 0, v171
	v_add_f32_e32 v177, v54, v55
	v_add_f32_e32 v179, v56, v57
	v_mov_b32_e32 v176, v50
	v_mov_b32_e32 v178, v51
	v_mov_b32_e32 v174, v52
	v_mov_b32_e32 v172, v53
	v_pk_add_f32 v[176:177], v[176:177], v[178:179]
	v_pk_add_f32 v[172:173], v[174:175], v[172:173]
	s_nop 0
	v_pk_add_f32 v[172:173], v[176:177], v[172:173]
	s_nop 0
	v_add_f32_e32 v171, v172, v173
	v_mov_b32_e32 v172, v171
	s_nop 1
	v_permlane16_swap_b32 v172, v171
	v_add_f32_e32 v171, v171, v172
	v_mov_b32_e32 v172, v171
	s_nop 1
	v_permlane32_swap_b32 v172, v171
	v_add_f32_e32 v171, v171, v172
	v_fmamk_f32 v173, v171, 0xbc800000, v141
	v_fmamk_f32 v175, v171, 0xbc800000, v139
	v_fmamk_f32 v172, v171, 0xbc800000, v140
	v_fmamk_f32 v174, v171, 0xbc800000, v138
	v_mul_f32_e32 v175, v175, v175
	v_mul_f32_e32 v173, v173, v173
	v_fmac_f32_e32 v175, v174, v174
	v_fmac_f32_e32 v173, v172, v172
	v_fmamk_f32 v174, v171, 0xbc800000, v93
	v_fmamk_f32 v176, v171, 0xbc800000, v91
	v_add_f32_e32 v172, v175, v173
	v_fmamk_f32 v173, v171, 0xbc800000, v92
	v_fmamk_f32 v175, v171, 0xbc800000, v90
	v_mul_f32_e32 v176, v176, v176
	v_mul_f32_e32 v174, v174, v174
	v_fmac_f32_e32 v176, v175, v175
	v_fmac_f32_e32 v174, v173, v173
	v_add_f32_e32 v173, v176, v174
	v_fmamk_f32 v174, v171, 0xbc800000, v57
	v_fmamk_f32 v176, v171, 0xbc800000, v55
	v_add_f32_e32 v172, v172, v173
	v_fmamk_f32 v173, v171, 0xbc800000, v56
	v_fmamk_f32 v175, v171, 0xbc800000, v54
	v_mul_f32_e32 v176, v176, v176
	v_mul_f32_e32 v174, v174, v174
	v_fmac_f32_e32 v176, v175, v175
	v_fmac_f32_e32 v174, v173, v173
	v_add_f32_e32 v173, v176, v174
	v_fmamk_f32 v174, v171, 0xbc800000, v53
	v_fmamk_f32 v176, v171, 0xbc800000, v51
	v_add_f32_e32 v172, v173, v172
	v_fmamk_f32 v173, v171, 0xbc800000, v52
	v_fmamk_f32 v175, v171, 0xbc800000, v50
	v_mul_f32_e32 v176, v176, v176
	v_mul_f32_e32 v174, v174, v174
	v_fmac_f32_e32 v176, v175, v175
	v_fmac_f32_e32 v174, v173, v173
	v_add_f32_e32 v173, v176, v174
	v_add_f32_e32 v172, v173, v172
	v_mov_b32_e32 v173, v172
	s_nop 1
	v_permlane16_swap_b32 v173, v172
	v_add_f32_e32 v172, v172, v173
	v_mov_b32_e32 v173, v172
	s_nop 1
	v_permlane32_swap_b32 v173, v172
	s_and_saveexec_b64 s[0:1], vcc
	s_cbranch_execz .LBB0_833
	v_mul_f32_e32 v174, 0x3c800000, v171
	v_add_f32_e32 v175, v172, v173
	ds_write_b64 v170, v[174:175] offset:5120
.LBB0_833:
	s_or_b64 exec, exec, s[0:1]
	v_mov_b32_e32 v172, v135
	v_mov_b32_e32 v173, v136
	v_mov_b32_e32 v174, v134
	v_mov_b32_e32 v175, v137
	v_pk_add_f32 v[172:173], v[172:173], v[174:175]
	v_mov_b32_e32 v174, v83
	v_mov_b32_e32 v175, v84
	v_mov_b32_e32 v176, v82
	v_mov_b32_e32 v177, v85
	v_pk_add_f32 v[174:175], v[174:175], v[176:177]
	v_add_f32_e32 v171, v172, v173
	v_pk_add_f32 v[174:175], v[174:175], v[174:175] op_sel_hi:[0,1]
	v_add_f32_e32 v173, 0, v171
	v_add_f32_e32 v177, v62, v63
	v_add_f32_e32 v179, v64, v65
	v_mov_b32_e32 v176, v58
	v_mov_b32_e32 v178, v59
	v_mov_b32_e32 v174, v60
	v_mov_b32_e32 v172, v61
	v_pk_add_f32 v[176:177], v[176:177], v[178:179]
	v_pk_add_f32 v[172:173], v[174:175], v[172:173]
	s_nop 0
	v_pk_add_f32 v[172:173], v[176:177], v[172:173]
	s_nop 0
	v_add_f32_e32 v171, v172, v173
	v_mov_b32_e32 v172, v171
	s_nop 1
	v_permlane16_swap_b32 v172, v171
	v_add_f32_e32 v171, v171, v172
	v_mov_b32_e32 v172, v171
	s_nop 1
	v_permlane32_swap_b32 v172, v171
	v_add_f32_e32 v171, v171, v172
	v_fmamk_f32 v173, v171, 0xbc800000, v137
	v_fmamk_f32 v175, v171, 0xbc800000, v135
	v_fmamk_f32 v172, v171, 0xbc800000, v136
	v_fmamk_f32 v174, v171, 0xbc800000, v134
	v_mul_f32_e32 v175, v175, v175
	v_mul_f32_e32 v173, v173, v173
	v_fmac_f32_e32 v175, v174, v174
	v_fmac_f32_e32 v173, v172, v172
	v_fmamk_f32 v174, v171, 0xbc800000, v85
	v_fmamk_f32 v176, v171, 0xbc800000, v83
	v_add_f32_e32 v172, v175, v173
	v_fmamk_f32 v173, v171, 0xbc800000, v84
	v_fmamk_f32 v175, v171, 0xbc800000, v82
	v_mul_f32_e32 v176, v176, v176
	v_mul_f32_e32 v174, v174, v174
	v_fmac_f32_e32 v176, v175, v175
	v_fmac_f32_e32 v174, v173, v173
	v_add_f32_e32 v173, v176, v174
	v_fmamk_f32 v174, v171, 0xbc800000, v65
	v_fmamk_f32 v176, v171, 0xbc800000, v63
	v_add_f32_e32 v172, v172, v173
	v_fmamk_f32 v173, v171, 0xbc800000, v64
	v_fmamk_f32 v175, v171, 0xbc800000, v62
	v_mul_f32_e32 v176, v176, v176
	v_mul_f32_e32 v174, v174, v174
	v_fmac_f32_e32 v176, v175, v175
	v_fmac_f32_e32 v174, v173, v173
	v_add_f32_e32 v173, v176, v174
	v_fmamk_f32 v174, v171, 0xbc800000, v61
	v_fmamk_f32 v176, v171, 0xbc800000, v59
	v_add_f32_e32 v172, v173, v172
	v_fmamk_f32 v173, v171, 0xbc800000, v60
	v_fmamk_f32 v175, v171, 0xbc800000, v58
	v_mul_f32_e32 v176, v176, v176
	v_mul_f32_e32 v174, v174, v174
	v_fmac_f32_e32 v176, v175, v175
	v_fmac_f32_e32 v174, v173, v173
	v_add_f32_e32 v173, v176, v174
	v_add_f32_e32 v172, v173, v172
	v_mov_b32_e32 v167, v172
	s_nop 1
	v_permlane16_swap_b32 v167, v172
	v_add_f32_e32 v167, v172, v167
	v_mov_b32_e32 v169, v167
	s_nop 1
	v_permlane32_swap_b32 v169, v167
	s_and_saveexec_b64 s[0:1], vcc
	s_cbranch_execz .LBB0_835
	v_mul_f32_e32 v172, 0x3c800000, v171
	v_add_f32_e32 v173, v167, v169
	ds_write_b64 v170, v[172:173] offset:5632
